# v36 plus even-tile staging waits counted (vmcnt 4/3 and 3/2) with one full vmcnt wait before each attention tile loop
# speedup vs baseline: 1.0002x; 1.0002x over previous
; __device__ __forceinline__ float bflo(unsigned w) { return __uint_as_float(w << 16); }
; __device__ __forceinline__ float bfhi(unsigned w) { return __uint_as_float(w & 0xffff0000u); }
; __device__ __forceinline__ float pairsum(float v) { auto rr = __builtin_amdgcn_permlane32_swap(__float_as_uint(v), __float_as_uint(v), false, false); return __uint_as_float(rr[0]) + __uint_as_float(rr[1]); }
;     constexpr int ND = (MODE == 2) ? 6 : 4, QP = 1536;
;     const int r32 = lane & 31, hi = lane >> 5;
; #pragma unroll
;     for (int qb = 0; qb < 2; ++qb) {
;         __builtin_amdgcn_sched_barrier(0);
;         const bf16_t* src = U.q + (size_t)(32 * qb + r32) * QP + 8 * hi;
;         u32x4 raw[ND];
; #pragma unroll
;         for (int d0 = 0; d0 < ND; ++d0) raw[d0] = *(const u32x4*)(src + 16 * d0);
;         int pos = U.tq0 + 32 * qb + r32; asm volatile("" : "+v"(pos));
;         if constexpr (MODE == 1) {
; #pragma unroll
;             for (int d0 = 0; d0 < ND; ++d0) qf[qb][d0] = __builtin_bit_cast(bf16x8, raw[d0]);
;         } else if constexpr (MODE == 0) {
;             float v[4][8]; float ss = 0.f;
; #pragma unroll
;             for (int d0 = 0; d0 < 4; ++d0)
; #pragma unroll
;                 for (int j = 0; j < 4; ++j) { const unsigned w = raw[d0][j]; v[d0][2 * j] = bflo(w); v[d0][2 * j + 1] = bfhi(w); ss += v[d0][2 * j] * v[d0][2 * j] + v[d0][2 * j + 1] * v[d0][2 * j + 1]; }
;             ss = pairsum(ss);
;             const float rstd = rsqrtf(ss * (1.0f / 64.0f) + EPSN) * C2_64;
; #pragma unroll
;             for (int d0 = 0; d0 < 4; ++d0)
; #pragma unroll
;                 for (int j = 0; j < 8; ++j) v[d0][j] *= rstd * U.gain[16 * d0 + 8 * hi + j];
;             const int row = pos >> 6, col = pos & 63;
; #pragma unroll
;             for (int j = 0; j < 8; ++j) {
;                 __builtin_amdgcn_sched_barrier(0);
;                 const float fi = hi ? invf_c(8 + j) : invf_c(j); float c, s;
;                 rope_cs(row, fi, c, s); { const float x1 = v[0][j], x2 = v[1][j]; v[0][j] = x1 * c - x2 * s; v[1][j] = x2 * c + x1 * s; }
;                 rope_cs(col, fi, c, s); { const float x1 = v[2][j], x2 = v[3][j]; v[2][j] = x1 * c - x2 * s; v[3][j] = x2 * c + x1 * s; }
;             }
.LBB0_436:
	s_add_u32 s46, s12, s46
	s_addc_u32 s47, s13, s47
	s_add_i32 s87, s87, s86
	s_add_u32 s4, s53, s88
	s_addc_u32 s5, s54, s87
	s_lshl_b32 s6, s85, 1
	s_add_u32 s10, s4, s6
	s_addc_u32 s11, s5, 0
	s_lshl_b64 s[6:7], s[44:45], 22
	s_add_u32 s4, s55, s6
	s_addc_u32 s5, s56, s7
	s_lshl_b32 s33, s84, 1
	s_add_u32 s4, s4, s33
	s_load_dwordx2 s[8:9], s[24:25], 0x30
	s_addc_u32 s5, s5, 0
	s_add_u32 s6, s57, s6
	s_addc_u32 s7, s58, s7
	s_lshl_b32 s33, s83, 1
	v_mbcnt_lo_u32_b32 v229, -1, 0
	v_mbcnt_hi_u32_b32 v229, -1, v229
	s_add_u32 s6, s6, s33
	v_lshrrev_b32_e32 v0, 2, v229
	v_and_b32_e32 v228, 63, v229
	v_and_b32_e32 v227, 31, v229
	v_and_b32_e32 v2, 8, v0
	s_addc_u32 s7, s7, 0
	v_cmp_gt_u32_e32 vcc, 32, v228
	v_mul_u32_u24_e32 v0, 0x600, v227
	v_lshlrev_b32_e32 v168, 1, v0
	v_lshl_add_u64 v[0:1], s[10:11], 0, v[168:169]
	v_lshlrev_b32_e32 v168, 1, v2
	v_lshl_add_u64 v[0:1], v[0:1], 0, v[168:169]
	v_or_b32_e32 v32, s82, v227
	global_load_dwordx4 v[20:23], v[0:1], off
	global_load_dwordx4 v[16:19], v[0:1], off offset:32
	global_load_dwordx4 v[28:31], v[0:1], off offset:64
	global_load_dwordx4 v[24:27], v[0:1], off offset:96
	v_cndmask_b32_e64 v93, v206, 1.0, vcc
	v_ashrrev_i32_e32 v33, 6, v32
	v_cvt_f32_i32_e32 v33, v33
	v_and_b32_e32 v32, 63, v32
	v_cvt_f32_ubyte0_e32 v32, v32
	v_cndmask_b32_e32 v95, v207, v208, vcc
	v_mul_f32_e32 v34, v93, v33
	v_mul_f32_e32 v35, 0.15915494, v34
	v_rndne_f32_e32 v35, v35
	v_fmac_f32_e32 v34, 0xc0c90fdb, v35
	v_fmac_f32_e32 v34, 0x343bbd2e, v35
	v_mul_f32_e32 v34, 0.15915494, v34
	v_sin_f32_e32 v74, v34
	v_cos_f32_e32 v76, v34
	v_mul_f32_e32 v34, v93, v32
	v_mul_f32_e32 v35, 0.15915494, v34
	v_rndne_f32_e32 v35, v35
	v_fmac_f32_e32 v34, 0xc0c90fdb, v35
	v_fmac_f32_e32 v34, 0x343bbd2e, v35
	v_mul_f32_e32 v34, 0.15915494, v34
	v_sin_f32_e32 v78, v34
	v_cos_f32_e32 v80, v34
	v_mul_f32_e32 v34, v95, v33
	v_mul_f32_e32 v35, 0.15915494, v34
	v_rndne_f32_e32 v35, v35
	v_fmac_f32_e32 v34, 0xc0c90fdb, v35
	v_fmac_f32_e32 v34, 0x343bbd2e, v35
	v_mul_f32_e32 v34, 0.15915494, v34
	v_sin_f32_e32 v75, v34
	v_cos_f32_e32 v77, v34
	v_mul_f32_e32 v34, v95, v32
	s_movk_i32 s33, 0x7c
	v_mul_f32_e32 v35, 0.15915494, v34
	v_bitop3_b32 v73, v229, s33, v203 bitop3:0xc8
	s_movk_i32 s33, 0xbc
	v_rndne_f32_e32 v35, v35
	v_lshlrev_b32_e32 v61, 2, v2
	v_bitop3_b32 v69, v229, 60, 28 bitop3:0xc8
	v_bitop3_b32 v92, v229, s33, v204 bitop3:0xc8
	s_movk_i32 s33, 0xfc
	v_fmac_f32_e32 v34, 0xc0c90fdb, v35
	s_waitcnt lgkmcnt(0)
	global_load_dwordx3 v[56:58], v61, s[8:9] offset:16
	global_load_dwordx4 v[12:15], v61, s[8:9]
	global_load_dwordx3 v[52:54], v61, s[8:9] offset:80
	global_load_dwordx4 v[8:11], v61, s[8:9] offset:64
	global_load_dwordx3 v[48:50], v61, s[8:9] offset:144
	global_load_dwordx4 v[4:7], v61, s[8:9] offset:128
	global_load_dwordx3 v[44:46], v61, s[8:9] offset:208
	global_load_dwordx4 v[0:3], v61, s[8:9] offset:192
	v_bitop3_b32 v94, v229, s33, v205 bitop3:0xc8
	global_load_dword v83, v69, s[8:9]
	global_load_dword v55, v73, s[8:9]
	global_load_dword v51, v92, s[8:9]
	global_load_dword v47, v94, s[8:9]
	v_fmac_f32_e32 v34, 0x343bbd2e, v35
	v_mul_f32_e32 v34, 0.15915494, v34
	v_cndmask_b32_e32 v105, v209, v210, vcc
	v_sin_f32_e32 v79, v34
	v_cos_f32_e32 v81, v34
	v_mul_f32_e32 v34, v105, v33
	v_mul_f32_e32 v35, 0.15915494, v34
	v_rndne_f32_e32 v35, v35
	v_fmac_f32_e32 v34, 0xc0c90fdb, v35
	v_fmac_f32_e32 v34, 0x343bbd2e, v35
	v_mul_f32_e32 v34, 0.15915494, v34
	v_sin_f32_e32 v84, v34
	v_cos_f32_e32 v86, v34
	v_mul_f32_e32 v34, v105, v32
	v_mul_f32_e32 v35, 0.15915494, v34
	v_rndne_f32_e32 v35, v35
	v_fmac_f32_e32 v34, 0xc0c90fdb, v35
	v_fmac_f32_e32 v34, 0x343bbd2e, v35
	v_mul_f32_e32 v34, 0.15915494, v34
	v_cndmask_b32_e32 v107, v211, v218, vcc
	v_sin_f32_e32 v88, v34
	v_cos_f32_e32 v90, v34
	v_mul_f32_e32 v34, v107, v33
	v_mul_f32_e32 v35, 0.15915494, v34
	v_rndne_f32_e32 v35, v35
	v_fmac_f32_e32 v34, 0xc0c90fdb, v35
	v_fmac_f32_e32 v34, 0x343bbd2e, v35
	v_mul_f32_e32 v34, 0.15915494, v34
	v_sin_f32_e32 v85, v34
	v_cos_f32_e32 v87, v34
	v_mul_f32_e32 v34, v107, v32
	v_mul_f32_e32 v35, 0.15915494, v34
	v_rndne_f32_e32 v35, v35
	v_fmac_f32_e32 v34, 0xc0c90fdb, v35
	v_fmac_f32_e32 v34, 0x343bbd2e, v35
	v_mul_f32_e32 v34, 0.15915494, v34
	s_waitcnt vmcnt(17)
	v_cndmask_b32_e32 v132, v219, v220, vcc
	v_sin_f32_e32 v89, v34
	v_cos_f32_e32 v91, v34
	v_mul_f32_e32 v34, v132, v33
	v_mul_f32_e32 v35, 0.15915494, v34
	v_rndne_f32_e32 v35, v35
	v_fmac_f32_e32 v34, 0xc0c90fdb, v35
	v_fmac_f32_e32 v34, 0x343bbd2e, v35
	v_mul_f32_e32 v34, 0.15915494, v34
	v_sin_f32_e32 v96, v34
	v_cos_f32_e32 v98, v34
	v_mul_f32_e32 v34, v132, v32
	v_mul_f32_e32 v35, 0.15915494, v34
	v_rndne_f32_e32 v35, v35
	v_fmac_f32_e32 v34, 0xc0c90fdb, v35
	v_fmac_f32_e32 v34, 0x343bbd2e, v35
	v_mul_f32_e32 v34, 0.15915494, v34
	v_cndmask_b32_e32 v134, v221, v222, vcc
	v_sin_f32_e32 v100, v34
	v_cos_f32_e32 v102, v34
	v_mul_f32_e32 v34, v134, v33
	v_mul_f32_e32 v35, 0.15915494, v34
	v_rndne_f32_e32 v35, v35
	v_fmac_f32_e32 v34, 0xc0c90fdb, v35
	v_fmac_f32_e32 v34, 0x343bbd2e, v35
	v_mul_f32_e32 v34, 0.15915494, v34
	v_sin_f32_e32 v97, v34
	v_cos_f32_e32 v99, v34
	v_mul_f32_e32 v34, v134, v32
	v_mul_f32_e32 v35, 0.15915494, v34
	v_rndne_f32_e32 v35, v35
	v_fmac_f32_e32 v34, 0xc0c90fdb, v35
	v_fmac_f32_e32 v34, 0x343bbd2e, v35
	v_mul_f32_e32 v34, 0.15915494, v34
	v_cndmask_b32_e32 v104, v223, v224, vcc
	v_sin_f32_e32 v101, v34
	v_cos_f32_e32 v103, v34
	v_mul_f32_e32 v34, v104, v33
	v_mul_f32_e32 v35, 0.15915494, v34
	v_rndne_f32_e32 v35, v35
	v_fmac_f32_e32 v34, 0xc0c90fdb, v35
	v_fmac_f32_e32 v34, 0x343bbd2e, v35
	v_mul_f32_e32 v34, 0.15915494, v34
	v_sin_f32_e32 v108, v34
	v_cos_f32_e32 v110, v34
	v_mul_f32_e32 v34, v104, v32
	v_mul_f32_e32 v35, 0.15915494, v34
	v_rndne_f32_e32 v35, v35
	v_fmac_f32_e32 v34, 0xc0c90fdb, v35
	v_fmac_f32_e32 v34, 0x343bbd2e, v35
	v_cndmask_b32_e32 v178, v225, v226, vcc
	v_mul_f32_e32 v34, 0.15915494, v34
	v_mul_f32_e32 v33, v178, v33
	s_waitcnt vmcnt(17)
; __device__ __forceinline__ float bflo(unsigned w) { return __uint_as_float(w << 16); }
; __device__ __forceinline__ float bfhi(unsigned w) { return __uint_as_float(w & 0xffff0000u); }
; __device__ __forceinline__ float pairsum(float v) { auto rr = __builtin_amdgcn_permlane32_swap(__float_as_uint(v), __float_as_uint(v), false, false); return __uint_as_float(rr[0]) + __uint_as_float(rr[1]); }
;     ...
;         const bf16_t* src = U.q + (size_t)(32 * qb + r32) * QP + 8 * hi;
;         u32x4 raw[ND];
; #pragma unroll
;         for (int d0 = 0; d0 < ND; ++d0) raw[d0] = *(const u32x4*)(src + 16 * d0);
;     ...
;             float v[4][8]; float ss = 0.f;
; #pragma unroll
;             for (int d0 = 0; d0 < 4; ++d0)
; #pragma unroll
;                 for (int j = 0; j < 4; ++j) { const unsigned w = raw[d0][j]; v[d0][2 * j] = bflo(w); v[d0][2 * j + 1] = bfhi(w); ss += v[d0][2 * j] * v[d0][2 * j] + v[d0][2 * j + 1] * v[d0][2 * j + 1]; }
;             ss = pairsum(ss);
;             const float rstd = rsqrtf(ss * (1.0f / 64.0f) + EPSN) * C2_64;
; #pragma unroll
;             for (int d0 = 0; d0 < 4; ++d0)
; #pragma unroll
;                 for (int j = 0; j < 8; ++j) v[d0][j] *= rstd * U.gain[16 * d0 + 8 * hi + j];
	v_sin_f32_e32 v112, v34
	v_cos_f32_e32 v114, v34
	v_mul_f32_e32 v34, 0.15915494, v33
	v_rndne_f32_e32 v34, v34
	v_fmac_f32_e32 v33, 0xc0c90fdb, v34
	v_fmac_f32_e32 v33, 0x343bbd2e, v34
	v_mul_f32_e32 v33, 0.15915494, v33
	v_mul_f32_e32 v32, v178, v32
	v_sin_f32_e32 v109, v33
	v_cos_f32_e32 v111, v33
	v_mul_f32_e32 v33, 0.15915494, v32
	v_rndne_f32_e32 v33, v33
	v_fmac_f32_e32 v32, 0xc0c90fdb, v33
	v_fmac_f32_e32 v32, 0x343bbd2e, v33
	v_mul_f32_e32 v32, 0.15915494, v32
	s_waitcnt vmcnt(13)
	v_and_b32_e32 v119, 0xffff0000, v31
	v_and_b32_e32 v121, 0xffff0000, v30
	v_sin_f32_e32 v113, v32
	v_cos_f32_e32 v115, v32
	v_lshlrev_b32_e32 v118, 16, v31
	v_lshlrev_b32_e32 v120, 16, v30
	v_mov_b32_e32 v32, v119
	v_mov_b32_e32 v33, v121
	s_waitcnt vmcnt(12)
	v_and_b32_e32 v117, 0xffff0000, v27
	v_mov_b32_e32 v30, v118
	v_mov_b32_e32 v31, v120
	v_pk_mul_f32 v[32:33], v[32:33], v[32:33]
	v_and_b32_e32 v123, 0xffff0000, v26
	v_lshlrev_b32_e32 v116, 16, v27
	v_pk_fma_f32 v[30:31], v[30:31], v[30:31], v[32:33]
	v_lshlrev_b32_e32 v122, 16, v26
	v_mov_b32_e32 v32, v117
	v_mov_b32_e32 v33, v123
	v_mov_b32_e32 v26, v116
	v_mov_b32_e32 v27, v122
	v_pk_mul_f32 v[32:33], v[32:33], v[32:33]
	v_and_b32_e32 v127, 0xffff0000, v29
	v_and_b32_e32 v129, 0xffff0000, v28
	v_pk_fma_f32 v[26:27], v[26:27], v[26:27], v[32:33]
	v_lshlrev_b32_e32 v126, 16, v29
	v_lshlrev_b32_e32 v128, 16, v28
	v_mov_b32_e32 v32, v127
	v_mov_b32_e32 v33, v129
	v_and_b32_e32 v125, 0xffff0000, v25
	v_mov_b32_e32 v28, v126
	v_mov_b32_e32 v29, v128
	v_pk_mul_f32 v[32:33], v[32:33], v[32:33]
	v_and_b32_e32 v131, 0xffff0000, v24
	v_and_b32_e32 v173, 0xffff0000, v21
	v_and_b32_e32 v177, 0xffff0000, v20
	v_lshlrev_b32_e32 v124, 16, v25
	v_pk_fma_f32 v[28:29], v[28:29], v[28:29], v[32:33]
	v_lshlrev_b32_e32 v130, 16, v24
	v_mov_b32_e32 v32, v125
	v_mov_b32_e32 v33, v131
	v_and_b32_e32 v165, 0xffff0000, v22
	v_lshlrev_b32_e32 v172, 16, v21
	v_mul_f32_e32 v36, v173, v173
	v_lshlrev_b32_e32 v176, 16, v20
	v_mul_f32_e32 v20, v177, v177
	v_mov_b32_e32 v24, v124
	v_mov_b32_e32 v25, v130
	v_pk_mul_f32 v[32:33], v[32:33], v[32:33]
	v_and_b32_e32 v161, 0xffff0000, v23
	v_and_b32_e32 v159, 0xffff0000, v19
	v_lshlrev_b32_e32 v164, 16, v22
	v_mul_f32_e32 v22, v165, v165
	v_and_b32_e32 v163, 0xffff0000, v18
	v_pk_fma_f32 v[36:37], v[172:173], v[172:173], v[36:37] op_sel_hi:[1,1,0]
	v_and_b32_e32 v167, 0xffff0000, v17
	v_pk_fma_f32 v[20:21], v[176:177], v[176:177], v[20:21] op_sel_hi:[1,1,0]
	v_and_b32_e32 v175, 0xffff0000, v16
	v_pk_fma_f32 v[24:25], v[24:25], v[24:25], v[32:33]
	v_lshlrev_b32_e32 v160, 16, v23
	v_mul_f32_e32 v32, v161, v161
	v_lshlrev_b32_e32 v158, 16, v19
	v_mul_f32_e32 v34, v159, v159
	v_pk_fma_f32 v[22:23], v[164:165], v[164:165], v[22:23] op_sel_hi:[1,1,0]
	v_lshlrev_b32_e32 v162, 16, v18
	v_mul_f32_e32 v18, v163, v163
	v_lshlrev_b32_e32 v166, 16, v17
	v_mul_f32_e32 v38, v167, v167
	v_lshlrev_b32_e32 v174, 16, v16
	v_mul_f32_e32 v16, v175, v175
	v_pk_add_f32 v[20:21], v[20:21], v[36:37]
	v_pk_fma_f32 v[32:33], v[160:161], v[160:161], v[32:33] op_sel_hi:[1,1,0]
	v_pk_fma_f32 v[34:35], v[158:159], v[158:159], v[34:35] op_sel_hi:[1,1,0]
	s_waitcnt vmcnt(11)
	v_mov_b32_e32 v82, v58
	v_pk_fma_f32 v[18:19], v[162:163], v[162:163], v[18:19] op_sel_hi:[1,1,0]
	v_pk_fma_f32 v[38:39], v[166:167], v[166:167], v[38:39] op_sel_hi:[1,1,0]
	v_pk_fma_f32 v[16:17], v[174:175], v[174:175], v[16:17] op_sel_hi:[1,1,0]
	v_pk_add_f32 v[20:21], v[22:23], v[20:21]
	s_nop 0
	v_pk_add_f32 v[20:21], v[32:33], v[20:21]
	s_nop 0
	v_pk_add_f32 v[16:17], v[16:17], v[20:21]
	s_nop 0
	v_pk_add_f32 v[16:17], v[38:39], v[16:17]
	s_nop 0
	v_pk_add_f32 v[16:17], v[18:19], v[16:17]
	s_nop 0
	v_pk_add_f32 v[16:17], v[34:35], v[16:17]
	s_nop 0
	v_pk_add_f32 v[16:17], v[28:29], v[16:17] op_sel:[1,0] op_sel_hi:[0,1]
	v_pk_add_f32 v[16:17], v[28:29], v[16:17]
	s_nop 0
	v_pk_add_f32 v[16:17], v[30:31], v[16:17] op_sel:[1,0] op_sel_hi:[0,1]
	v_pk_add_f32 v[16:17], v[30:31], v[16:17]
	s_nop 0
	v_pk_add_f32 v[16:17], v[24:25], v[16:17] op_sel:[1,0] op_sel_hi:[0,1]
	v_pk_add_f32 v[16:17], v[24:25], v[16:17]
	s_nop 0
	v_pk_add_f32 v[16:17], v[26:27], v[16:17] op_sel:[1,0] op_sel_hi:[0,1]
	v_pk_add_f32 v[192:193], v[26:27], v[16:17]
	s_nop 0
	v_mov_b32_e32 v65, v192
	s_nop 1
	v_permlane32_swap_b32_e32 v192, v65
	v_or_b32_e32 v18, 32, v228
	v_mul_u32_u24_e32 v16, 0x600, v18
	v_lshlrev_b32_e32 v16, 1, v16
	v_mov_b32_e32 v17, v169
	v_lshl_add_u64 v[16:17], s[10:11], 0, v[16:17]
	v_lshl_add_u64 v[16:17], v[16:17], 0, v[168:169]
	global_load_dwordx4 v[36:39], v[16:17], off
	global_load_dwordx4 v[32:35], v[16:17], off offset:32
	global_load_dwordx4 v[194:197], v[16:17], off offset:64
	global_load_dwordx4 v[40:43], v[16:17], off offset:96
	v_or_b32_e32 v106, s82, v18
	global_load_dwordx3 v[58:60], v61, s[8:9] offset:16
	global_load_dwordx4 v[16:19], v61, s[8:9]
	global_load_dwordx3 v[62:64], v61, s[8:9] offset:80
	global_load_dwordx4 v[20:23], v61, s[8:9] offset:64
	global_load_dwordx3 v[66:68], v61, s[8:9] offset:144
	global_load_dwordx4 v[24:27], v61, s[8:9] offset:128
	global_load_dwordx3 v[70:72], v61, s[8:9] offset:208
	global_load_dwordx4 v[28:31], v61, s[8:9] offset:192
	s_nop 0
	global_load_dword v69, v69, s[8:9]
	s_nop 0
	global_load_dword v61, v73, s[8:9]
	global_load_dword v133, v92, s[8:9]
	s_nop 0
	global_load_dword v73, v94, s[8:9]
	v_and_b32_e32 v92, 63, v106
	v_cvt_f32_ubyte0_e32 v168, v92
	v_mul_f32_e32 v92, v104, v168
	v_mul_f32_e32 v94, 0.15915494, v92
	v_rndne_f32_e32 v94, v94
	v_fmac_f32_e32 v92, 0xc0c90fdb, v94
	v_fmac_f32_e32 v92, 0x343bbd2e, v94
	v_ashrrev_i32_e32 v94, 6, v106
	v_mul_f32_e32 v135, v134, v168
; __device__ __forceinline__ float bflo(unsigned w) { return __uint_as_float(w << 16); }
; __device__ __forceinline__ float bfhi(unsigned w) { return __uint_as_float(w & 0xffff0000u); }
; __device__ __forceinline__ float pairsum(float v) { auto rr = __builtin_amdgcn_permlane32_swap(__float_as_uint(v), __float_as_uint(v), false, false); return __uint_as_float(rr[0]) + __uint_as_float(rr[1]); }
;     ...
;             for (int d0 = 0; d0 < 4; ++d0)
; #pragma unroll
;                 for (int j = 0; j < 4; ++j) { const unsigned w = raw[d0][j]; v[d0][2 * j] = bflo(w); v[d0][2 * j + 1] = bfhi(w); ss += v[d0][2 * j] * v[d0][2 * j] + v[d0][2 * j + 1] * v[d0][2 * j + 1]; }
;             ss = pairsum(ss);
;             const float rstd = rsqrtf(ss * (1.0f / 64.0f) + EPSN) * C2_64;
; #pragma unroll
;             for (int d0 = 0; d0 < 4; ++d0)
; #pragma unroll
;                 for (int j = 0; j < 8; ++j) v[d0][j] *= rstd * U.gain[16 * d0 + 8 * hi + j];
;             const int row = pos >> 6, col = pos & 63;
; #pragma unroll
;             for (int j = 0; j < 8; ++j) {
;                 __builtin_amdgcn_sched_barrier(0);
;                 const float fi = hi ? invf_c(8 + j) : invf_c(j); float c, s;
;                 rope_cs(row, fi, c, s); { const float x1 = v[0][j], x2 = v[1][j]; v[0][j] = x1 * c - x2 * s; v[1][j] = x2 * c + x1 * s; }
;                 rope_cs(col, fi, c, s); { const float x1 = v[2][j], x2 = v[3][j]; v[2][j] = x1 * c - x2 * s; v[3][j] = x2 * c + x1 * s; }
;             }
	v_cvt_f32_i32_e32 v179, v94
	v_mul_f32_e32 v136, 0.15915494, v135
	v_rndne_f32_e32 v136, v136
	v_fmac_f32_e32 v135, 0xc0c90fdb, v136
	v_fmac_f32_e32 v135, 0x343bbd2e, v136
	v_mul_f32_e32 v136, 0.15915494, v135
	v_mul_f32_e32 v134, v134, v179
	v_cos_f32_e32 v135, v136
	v_sin_f32_e32 v137, v136
	v_mul_f32_e32 v136, 0.15915494, v134
	v_rndne_f32_e32 v136, v136
	v_fmac_f32_e32 v134, 0xc0c90fdb, v136
	v_fmac_f32_e32 v134, 0x343bbd2e, v136
	v_mul_f32_e32 v134, 0.15915494, v134
	v_cos_f32_e32 v139, v134
	v_sin_f32_e32 v141, v134
	v_mul_f32_e32 v134, v132, v168
	v_mul_f32_e32 v132, v132, v179
	v_mul_f32_e32 v138, 0.15915494, v132
	v_rndne_f32_e32 v138, v138
	v_fmac_f32_e32 v132, 0xc0c90fdb, v138
	v_fmac_f32_e32 v132, 0x343bbd2e, v138
	v_mul_f32_e32 v132, 0.15915494, v132
	v_cos_f32_e32 v138, v132
	v_sin_f32_e32 v140, v132
	v_mul_f32_e32 v132, v107, v168
	v_mul_f32_e32 v142, 0.15915494, v132
	v_rndne_f32_e32 v142, v142
	v_fmac_f32_e32 v132, 0xc0c90fdb, v142
	v_fmac_f32_e32 v132, 0x343bbd2e, v142
	v_mul_f32_e32 v132, 0.15915494, v132
	v_mul_f32_e32 v107, v107, v179
	v_cos_f32_e32 v143, v132
	v_sin_f32_e32 v145, v132
	v_mul_f32_e32 v132, 0.15915494, v107
	v_rndne_f32_e32 v132, v132
	v_fmac_f32_e32 v107, 0xc0c90fdb, v132
	v_fmac_f32_e32 v107, 0x343bbd2e, v132
	v_mul_f32_e32 v107, 0.15915494, v107
	v_cos_f32_e32 v147, v107
	v_sin_f32_e32 v151, v107
	v_mul_f32_e32 v107, v105, v168
	v_mul_f32_e32 v132, 0.15915494, v107
	v_rndne_f32_e32 v132, v132
	v_fmac_f32_e32 v107, 0xc0c90fdb, v132
	v_fmac_f32_e32 v107, 0x343bbd2e, v132
	v_mul_f32_e32 v107, 0.15915494, v107
	v_mul_f32_e32 v105, v105, v179
	v_cos_f32_e32 v142, v107
	v_sin_f32_e32 v144, v107
	v_mul_f32_e32 v107, 0.15915494, v105
	v_rndne_f32_e32 v107, v107
	v_fmac_f32_e32 v105, 0xc0c90fdb, v107
	v_fmac_f32_e32 v105, 0x343bbd2e, v107
	v_mul_f32_e32 v105, 0.15915494, v105
	v_cos_f32_e32 v146, v105
	v_sin_f32_e32 v150, v105
	v_mul_f32_e32 v105, v95, v168
	v_mul_f32_e32 v107, 0.15915494, v105
	v_rndne_f32_e32 v107, v107
	v_fmac_f32_e32 v105, 0xc0c90fdb, v107
	v_fmac_f32_e32 v105, 0x343bbd2e, v107
	v_mul_f32_e32 v105, 0.15915494, v105
	v_mul_f32_e32 v95, v95, v179
	v_cos_f32_e32 v153, v105
	v_sin_f32_e32 v155, v105
	v_mul_f32_e32 v105, 0.15915494, v95
	v_rndne_f32_e32 v105, v105
	v_fmac_f32_e32 v95, 0xc0c90fdb, v105
	v_fmac_f32_e32 v95, 0x343bbd2e, v105
	v_mul_f32_e32 v95, 0.15915494, v95
	v_cos_f32_e32 v149, v95
	v_sin_f32_e32 v157, v95
	v_mul_f32_e32 v95, v93, v168
	v_mul_f32_e32 v105, 0.15915494, v95
	v_rndne_f32_e32 v105, v105
	v_fmac_f32_e32 v95, 0xc0c90fdb, v105
	v_fmac_f32_e32 v95, 0x343bbd2e, v105
	v_mul_f32_e32 v95, 0.15915494, v95
	v_mul_f32_e32 v93, v93, v179
	v_cos_f32_e32 v152, v95
	v_sin_f32_e32 v154, v95
	v_mul_f32_e32 v95, 0.15915494, v93
	v_rndne_f32_e32 v95, v95
	v_fmac_f32_e32 v93, 0xc0c90fdb, v95
	v_fmac_f32_e32 v93, 0x343bbd2e, v95
	v_mul_f32_e32 v93, 0.15915494, v93
	v_cos_f32_e32 v148, v93
	v_sin_f32_e32 v156, v93
	v_mul_f32_e32 v93, v178, v179
	v_mul_f32_e32 v95, 0.15915494, v93
	v_rndne_f32_e32 v95, v95
	v_fmac_f32_e32 v93, 0xc0c90fdb, v95
	v_fmac_f32_e32 v93, 0x343bbd2e, v95
	v_mul_f32_e32 v104, v104, v179
	v_mul_f32_e32 v93, 0.15915494, v93
	s_waitcnt vmcnt(13)
	v_and_b32_e32 v179, 0xffff0000, v197
	v_and_b32_e32 v183, 0xffff0000, v196
	v_sin_f32_e32 v105, v93
	v_cos_f32_e32 v107, v93
	v_mul_f32_e32 v93, v178, v168
	v_lshlrev_b32_e32 v178, 16, v197
	v_lshlrev_b32_e32 v182, 16, v196
	v_mov_b32_e32 v186, v179
	v_mov_b32_e32 v187, v183
	v_mov_b32_e32 v184, v178
	v_mov_b32_e32 v185, v182
	v_pk_mul_f32 v[186:187], v[186:187], v[186:187]
	s_waitcnt vmcnt(12)
	v_and_b32_e32 v181, 0xffff0000, v43
	v_pk_fma_f32 v[230:231], v[184:185], v[184:185], v[186:187]
	v_and_b32_e32 v187, 0xffff0000, v42
	v_lshlrev_b32_e32 v180, 16, v43
	v_lshlrev_b32_e32 v186, 16, v42
	v_mov_b32_e32 v184, v181
	v_mov_b32_e32 v185, v187
	v_mov_b32_e32 v42, v180
	v_mov_b32_e32 v43, v186
	v_pk_mul_f32 v[184:185], v[184:185], v[184:185]
	v_and_b32_e32 v189, 0xffff0000, v41
	v_pk_fma_f32 v[232:233], v[42:43], v[42:43], v[184:185]
	v_and_b32_e32 v185, 0xffff0000, v195
	v_and_b32_e32 v43, 0xffff0000, v194
	v_lshlrev_b32_e32 v184, 16, v195
	v_lshlrev_b32_e32 v42, 16, v194
	v_mov_b32_e32 v194, v185
	v_mov_b32_e32 v195, v43
	v_mov_b32_e32 v190, v184
	v_mov_b32_e32 v191, v42
	v_pk_mul_f32 v[194:195], v[194:195], v[194:195]
	v_lshlrev_b32_e32 v188, 16, v41
	v_pk_fma_f32 v[234:235], v[190:191], v[190:191], v[194:195]
	v_and_b32_e32 v191, 0xffff0000, v40
	v_lshlrev_b32_e32 v190, 16, v40
	v_mov_b32_e32 v194, v189
	v_mov_b32_e32 v195, v191
	v_and_b32_e32 v199, 0xffff0000, v34
	v_mul_f32_e32 v106, 0.15915494, v104
	v_mul_f32_e32 v136, 0.15915494, v134
	v_mov_b32_e32 v40, v188
	v_mov_b32_e32 v41, v190
	v_pk_mul_f32 v[194:195], v[194:195], v[194:195]
	v_and_b32_e32 v197, 0xffff0000, v38
	v_lshlrev_b32_e32 v198, 16, v34
	v_mul_f32_e32 v34, v199, v199
	v_rndne_f32_e32 v106, v106
	v_rndne_f32_e32 v136, v136
	v_pk_fma_f32 v[236:237], v[40:41], v[40:41], v[194:195]
	v_lshlrev_b32_e32 v194, 16, v35
	v_and_b32_e32 v195, 0xffff0000, v35
	v_lshlrev_b32_e32 v196, 16, v38
	v_mul_f32_e32 v38, v197, v197
	v_pk_fma_f32 v[244:245], v[198:199], v[198:199], v[34:35] op_sel_hi:[1,1,0]
	v_and_b32_e32 v35, 0xffff0000, v37
	v_fmac_f32_e32 v104, 0xc0c90fdb, v106
	v_fmac_f32_e32 v134, 0xc0c90fdb, v136
	v_pk_fma_f32 v[242:243], v[196:197], v[196:197], v[38:39] op_sel_hi:[1,1,0]
	v_lshlrev_b32_e32 v34, 16, v37
	v_mul_f32_e32 v38, v35, v35
	v_and_b32_e32 v201, 0xffff0000, v33
	v_fmac_f32_e32 v104, 0x343bbd2e, v106
	v_fmac_f32_e32 v134, 0x343bbd2e, v136
	v_pk_fma_f32 v[246:247], v[34:35], v[34:35], v[38:39] op_sel_hi:[1,1,0]
	v_lshlrev_b32_e32 v200, 16, v33
	v_mul_f32_e32 v38, v201, v201
	v_mul_f32_e32 v104, 0.15915494, v104
	v_mul_f32_e32 v136, 0.15915494, v134
	v_mul_f32_e32 v95, 0.15915494, v93
	v_lshlrev_b32_e32 v40, 16, v39
	v_and_b32_e32 v41, 0xffff0000, v39
	v_pk_fma_f32 v[248:249], v[200:201], v[200:201], v[38:39] op_sel_hi:[1,1,0]
	v_and_b32_e32 v39, 0xffff0000, v36
	v_cos_f32_e32 v106, v104
	v_sin_f32_e32 v104, v104
	v_cos_f32_e32 v134, v136
	v_sin_f32_e32 v136, v136
	v_rndne_f32_e32 v95, v95
	v_lshlrev_b32_e32 v38, 16, v36
	v_mul_f32_e32 v36, v39, v39
	v_fmac_f32_e32 v93, 0xc0c90fdb, v95
	s_waitcnt vmcnt(7)
; __device__ __forceinline__ unsigned pk(float lo, float hi) { f32x2_t v = {lo, hi}; bf16x2_t b = __builtin_convertvector(v, bf16x2_t); return __builtin_bit_cast(unsigned, b); }
; __device__ __forceinline__ float pairsum(float v) { auto rr = __builtin_amdgcn_permlane32_swap(__float_as_uint(v), __float_as_uint(v), false, false); return __uint_as_float(rr[0]) + __uint_as_float(rr[1]); }
;     ...
;             ss = pairsum(ss);
;             const float rstd = rsqrtf(ss * (1.0f / 64.0f) + EPSN) * C2_64;
; #pragma unroll
;             for (int d0 = 0; d0 < 4; ++d0)
; #pragma unroll
;                 for (int j = 0; j < 8; ++j) v[d0][j] *= rstd * U.gain[16 * d0 + 8 * hi + j];
;             const int row = pos >> 6, col = pos & 63;
; #pragma unroll
;             for (int j = 0; j < 8; ++j) {
;                 __builtin_amdgcn_sched_barrier(0);
;                 const float fi = hi ? invf_c(8 + j) : invf_c(j); float c, s;
;                 rope_cs(row, fi, c, s); { const float x1 = v[0][j], x2 = v[1][j]; v[0][j] = x1 * c - x2 * s; v[1][j] = x2 * c + x1 * s; }
;                 rope_cs(col, fi, c, s); { const float x1 = v[2][j], x2 = v[3][j]; v[2][j] = x1 * c - x2 * s; v[3][j] = x2 * c + x1 * s; }
;             }
; #pragma unroll
;             for (int d0 = 0; d0 < 4; ++d0) { u32x4 w; w.x = pk(v[d0][0], v[d0][1]); w.y = pk(v[d0][2], v[d0][3]); w.z = pk(v[d0][4], v[d0][5]); w.w = pk(v[d0][6], v[d0][7]); qf[qb][d0] = __builtin_bit_cast(bf16x8, w); }
	v_mov_b32_e32 v132, v68
	v_mul_f32_e32 v68, v41, v41
	v_pk_fma_f32 v[250:251], v[38:39], v[38:39], v[36:37] op_sel_hi:[1,1,0]
	v_and_b32_e32 v37, 0xffff0000, v32
	v_fmac_f32_e32 v93, 0x343bbd2e, v95
	s_waitcnt vmcnt(3)
	v_pk_fma_f32 v[238:239], v[40:41], v[40:41], v[68:69] op_sel_hi:[1,1,0]
	v_mul_f32_e32 v68, v195, v195
	v_lshlrev_b32_e32 v36, 16, v32
	v_mul_f32_e32 v32, v37, v37
	v_mul_f32_e32 v92, 0.15915494, v92
	v_mul_f32_e32 v95, 0.15915494, v93
	v_pk_fma_f32 v[240:241], v[194:195], v[194:195], v[68:69] op_sel_hi:[1,1,0]
	v_mov_b32_e32 v68, v60
	v_mov_b32_e32 v60, v64
	v_pk_fma_f32 v[32:33], v[36:37], v[36:37], v[32:33] op_sel_hi:[1,1,0]
	v_pk_add_f32 v[246:247], v[250:251], v[246:247]
	v_cos_f32_e32 v94, v92
	v_sin_f32_e32 v92, v92
	v_sin_f32_e32 v93, v95
	v_cos_f32_e32 v95, v95
	v_pk_add_f32 v[242:243], v[242:243], v[246:247]
	s_nop 0
	v_pk_add_f32 v[238:239], v[238:239], v[242:243]
	s_mov_b32 s8, 0x3c800000
	v_pk_add_f32 v[32:33], v[32:33], v[238:239]
	s_mov_b32 s33, 0
	v_pk_add_f32 v[32:33], v[248:249], v[32:33]
	s_nop 0
	v_pk_add_f32 v[32:33], v[244:245], v[32:33]
	s_nop 0
	v_pk_add_f32 v[32:33], v[240:241], v[32:33]
	s_nop 0
	v_pk_add_f32 v[32:33], v[234:235], v[32:33] op_sel:[1,0] op_sel_hi:[0,1]
	v_pk_add_f32 v[32:33], v[234:235], v[32:33]
	s_nop 0
	v_pk_add_f32 v[32:33], v[230:231], v[32:33] op_sel:[1,0] op_sel_hi:[0,1]
	v_pk_add_f32 v[32:33], v[230:231], v[32:33]
	s_nop 0
	v_pk_add_f32 v[32:33], v[236:237], v[32:33] op_sel:[1,0] op_sel_hi:[0,1]
	v_pk_add_f32 v[32:33], v[236:237], v[32:33]
	s_nop 0
	v_pk_add_f32 v[32:33], v[232:233], v[32:33] op_sel:[1,0] op_sel_hi:[0,1]
	v_pk_add_f32 v[32:33], v[232:233], v[32:33]
	s_nop 0
	v_mov_b32_e32 v64, v32
	s_nop 1
	v_permlane32_swap_b32_e32 v32, v64
	v_mov_b32_e32 v33, v192
	v_pk_add_f32 v[32:33], v[32:33], v[64:65]
	s_nop 0
	v_pk_fma_f32 v[32:33], v[32:33], s[8:9], v[170:171] op_sel_hi:[1,0,0]
	s_nop 0
	v_mul_f32_e32 v64, 0x4b800000, v33
	v_cmp_gt_f32_e32 vcc, s71, v33
	s_nop 1
	v_cndmask_b32_e32 v33, v33, v64, vcc
	v_rsq_f32_e32 v33, v33
	s_nop 0
	v_mul_f32_e32 v64, 0x45800000, v33
	v_cndmask_b32_e32 v33, v33, v64, vcc
	v_mul_f32_e32 v64, 0x3e38aa3b, v33
	v_pk_mul_f32 v[8:9], v[8:9], v[64:65] op_sel_hi:[1,0]
	v_pk_mul_f32 v[12:13], v[12:13], v[64:65] op_sel_hi:[1,0]
	v_pk_mul_f32 v[8:9], v[8:9], v[174:175]
	v_pk_mul_f32 v[12:13], v[12:13], v[176:177]
	v_pk_mul_f32 v[14:15], v[14:15], v[64:65] op_sel_hi:[1,0]
	v_pk_mul_f32 v[56:57], v[56:57], v[64:65] op_sel_hi:[1,0]
	v_pk_mul_f32 v[82:83], v[82:83], v[64:65] op_sel_hi:[1,0]
	v_pk_mul_f32 v[10:11], v[64:65], v[10:11] op_sel_hi:[0,1]
	v_pk_mul_f32 v[52:53], v[64:65], v[52:53] op_sel_hi:[0,1]
	v_pk_mul_f32 v[54:55], v[64:65], v[54:55] op_sel_hi:[0,1]
	v_pk_mul_f32 v[4:5], v[64:65], v[4:5] op_sel_hi:[0,1]
	v_pk_mul_f32 v[6:7], v[64:65], v[6:7] op_sel_hi:[0,1]
	v_pk_mul_f32 v[48:49], v[64:65], v[48:49] op_sel_hi:[0,1]
	v_pk_mul_f32 v[50:51], v[64:65], v[50:51] op_sel_hi:[0,1]
	v_pk_mul_f32 v[0:1], v[64:65], v[0:1] op_sel_hi:[0,1]
	v_pk_mul_f32 v[2:3], v[64:65], v[2:3] op_sel_hi:[0,1]
	v_pk_mul_f32 v[44:45], v[64:65], v[44:45] op_sel_hi:[0,1]
	v_pk_mul_f32 v[46:47], v[64:65], v[46:47] op_sel_hi:[0,1]
	v_pk_mul_f32 v[64:65], v[74:75], v[8:9]
	v_pk_mul_f32 v[0:1], v[0:1], v[130:131]
	v_pk_fma_f32 v[64:65], v[76:77], v[12:13], v[64:65] neg_lo:[0,0,1] neg_hi:[0,0,1]
	v_pk_mul_f32 v[12:13], v[74:75], v[12:13]
	v_pk_mul_f32 v[10:11], v[10:11], v[166:167]
	v_pk_mul_f32 v[4:5], v[4:5], v[128:129]
	v_pk_fma_f32 v[8:9], v[76:77], v[8:9], v[12:13]
	v_pk_mul_f32 v[12:13], v[78:79], v[0:1]
	v_pk_mul_f32 v[0:1], v[80:81], v[0:1]
	v_pk_mul_f32 v[14:15], v[14:15], v[172:173]
	v_pk_mul_f32 v[2:3], v[2:3], v[124:125]
	v_pk_fma_f32 v[74:75], v[80:81], v[4:5], v[12:13] neg_lo:[0,0,1] neg_hi:[0,0,1]
	v_pk_fma_f32 v[76:77], v[78:79], v[4:5], v[0:1]
	v_pk_mul_f32 v[4:5], v[86:87], v[10:11]
	v_pk_mul_f32 v[52:53], v[52:53], v[162:163]
	v_pk_mul_f32 v[6:7], v[6:7], v[126:127]
	v_pk_mul_f32 v[0:1], v[84:85], v[10:11]
	v_pk_fma_f32 v[78:79], v[84:85], v[14:15], v[4:5]
	v_pk_mul_f32 v[4:5], v[88:89], v[2:3]
	v_pk_mul_f32 v[56:57], v[56:57], v[164:165]
	v_pk_mul_f32 v[44:45], v[44:45], v[122:123]
	v_pk_fma_f32 v[0:1], v[86:87], v[14:15], v[0:1] neg_lo:[0,0,1] neg_hi:[0,0,1]
	v_pk_fma_f32 v[80:81], v[90:91], v[6:7], v[4:5] neg_lo:[0,0,1] neg_hi:[0,0,1]
	v_pk_mul_f32 v[2:3], v[90:91], v[2:3]
	v_pk_mul_f32 v[4:5], v[98:99], v[52:53]
	v_pk_mul_f32 v[54:55], v[54:55], v[158:159]
	v_pk_mul_f32 v[48:49], v[48:49], v[120:121]
	v_pk_mul_f32 v[46:47], v[46:47], v[116:117]
	v_pk_fma_f32 v[84:85], v[88:89], v[6:7], v[2:3]
	v_pk_mul_f32 v[2:3], v[96:97], v[52:53]
	v_pk_fma_f32 v[52:53], v[96:97], v[56:57], v[4:5]
	v_pk_mul_f32 v[4:5], v[100:101], v[44:45]
	v_cvt_pk_bf16_f32 v117, v0, v1
	v_add_u32_e32 v0, s36, v229
	v_lshlrev_b32_e32 v1, 4, v229
	v_pk_mul_f32 v[82:83], v[82:83], v[160:161]
	v_pk_fma_f32 v[2:3], v[98:99], v[56:57], v[2:3] neg_lo:[0,0,1] neg_hi:[0,0,1]
	v_pk_fma_f32 v[56:57], v[102:103], v[48:49], v[4:5] neg_lo:[0,0,1] neg_hi:[0,0,1]
	v_pk_mul_f32 v[4:5], v[102:103], v[44:45]
	v_pk_mul_f32 v[6:7], v[110:111], v[54:55]
	v_ashrrev_i32_e32 v33, 3, v0
	v_and_b32_e32 v86, 0x70, v1
	v_pk_mul_f32 v[50:51], v[50:51], v[118:119]
	v_pk_fma_f32 v[44:45], v[100:101], v[48:49], v[4:5]
	v_pk_fma_f32 v[48:49], v[108:109], v[82:83], v[6:7]
	v_pk_mul_f32 v[6:7], v[112:113], v[46:47]
	v_lshl_or_b32 v168, v33, 8, v86
	v_pk_mul_f32 v[4:5], v[108:109], v[54:55]
	v_pk_fma_f32 v[54:55], v[114:115], v[50:51], v[6:7] neg_lo:[0,0,1] neg_hi:[0,0,1]
	v_pk_mul_f32 v[6:7], v[114:115], v[46:47]
	v_cvt_pk_bf16_f32 v116, v64, v65
	v_lshl_add_u64 v[64:65], s[4:5], 0, v[168:169]
; __device__ __forceinline__ unsigned pk(float lo, float hi) { f32x2_t v = {lo, hi}; bf16x2_t b = __builtin_convertvector(v, bf16x2_t); return __builtin_bit_cast(unsigned, b); }
; #define BAR_LDS() asm volatile("s_waitcnt lgkmcnt(0)\n\ts_barrier" ::: "memory")
; #define ATT_LOADS(RK, RR, RV, tt) do { RK = *(const u32x4*)((const char*)(U.k + (size_t)(tt) * 64 * KP) + kgo); if (MODE == 2) RR = *(const u32x2*)((const char*)(U.kr + (size_t)(tt) * 64 * 32) + krgo); \
;         RV = *(const u32x4*)((const char*)(U.vt + (size_t)(tt) * VTS) + vgo); } while (0)
;     ...
;             const float rstd = rsqrtf(ss * (1.0f / 64.0f) + EPSN) * C2_64;
; #pragma unroll
;             for (int d0 = 0; d0 < 4; ++d0)
; #pragma unroll
;                 for (int j = 0; j < 8; ++j) v[d0][j] *= rstd * U.gain[16 * d0 + 8 * hi + j];
;             const int row = pos >> 6, col = pos & 63;
; #pragma unroll
;             for (int j = 0; j < 8; ++j) {
;                 __builtin_amdgcn_sched_barrier(0);
;                 const float fi = hi ? invf_c(8 + j) : invf_c(j); float c, s;
;                 rope_cs(row, fi, c, s); { const float x1 = v[0][j], x2 = v[1][j]; v[0][j] = x1 * c - x2 * s; v[1][j] = x2 * c + x1 * s; }
;                 rope_cs(col, fi, c, s); { const float x1 = v[2][j], x2 = v[3][j]; v[2][j] = x1 * c - x2 * s; v[3][j] = x2 * c + x1 * s; }
;             }
; #pragma unroll
;             for (int d0 = 0; d0 < 4; ++d0) { u32x4 w; w.x = pk(v[d0][0], v[d0][1]); w.y = pk(v[d0][2], v[d0][3]); w.z = pk(v[d0][4], v[d0][5]); w.w = pk(v[d0][6], v[d0][7]); qf[qb][d0] = __builtin_bit_cast(bf16x8, w); }
; template <int MODE, bool FAST> __device__ __forceinline__ bool attn_unit(LAS unsigned char* lds, const AttU& U, const int wv) {
;     ...
;     const int krow = tid >> 3, kc = tid & 7;
;     const unsigned kgo = (unsigned)(krow * KP + kc * 8) * 2u, krgo = (unsigned)(krow * 32 + kc * 4) * 2u, vgo = (unsigned)tid * 16u;
;     const unsigned kdst = krow * KSTR + kc * 16, krdst = krow * KSTR + 128 + kc * 8, vdst = 64 * KSTR + krow * VSTR + kc * 16;
;     u32x4 rk, rv, rk2, rv2; u32x2 rr = {0u, 0u}, rr2 = {0u, 0u};
;     ...
;     const int NT = U.kt1 - U.kt0;
;     ATT_LOAD(U.kt0); ATT_STORE(0);
;     if (NT > 1) { ATT_LOAD(U.kt0 + 1); ATT_STORE(1); }
;     if (NT > 2) ATT_LOAD(U.kt0 + 2);
;     if constexpr (FAST) { if (NT > 3) ATT_LOADS(rk2, rr2, rv2, U.kt0 + 3); }
;     BAR_LDS();
	v_pk_fma_f32 v[46:47], v[112:113], v[50:51], v[6:7]
	v_cvt_pk_bf16_f32 v120, v8, v9
	v_lshlrev_b32_e32 v50, 4, v0
	v_mov_b32_e32 v51, v169
	v_add_co_u32_e32 v8, vcc, s72, v64
	v_pk_fma_f32 v[4:5], v[110:111], v[82:83], v[4:5] neg_lo:[0,0,1] neg_hi:[0,0,1]
	v_lshl_add_u64 v[82:83], s[6:7], 0, v[50:51]
	v_addc_co_u32_e32 v9, vcc, 0, v65, vcc
	v_add_co_u32_e32 v12, vcc, s72, v82
	v_cvt_pk_bf16_f32 v118, v2, v3
	s_nop 0
	v_addc_co_u32_e32 v13, vcc, 0, v83, vcc
	v_cvt_pk_bf16_f32 v119, v4, v5
	global_load_dwordx4 v[0:3], v168, s[4:5]
	global_load_dwordx4 v[4:7], v50, s[6:7]
	s_nop 0
	global_load_dwordx4 v[8:11], v[8:9], off
	s_nop 0
	global_load_dwordx4 v[12:15], v[12:13], off
	v_cvt_pk_bf16_f32 v123, v48, v49
	v_mul_f32_e32 v48, 0x4b800000, v32
	v_cmp_gt_f32_e32 vcc, s71, v32
	v_cvt_pk_bf16_f32 v130, v44, v45
	v_cvt_pk_bf16_f32 v122, v52, v53
	v_cndmask_b32_e32 v32, v32, v48, vcc
	v_rsq_f32_e32 v32, v32
	v_cvt_pk_bf16_f32 v126, v56, v57
	v_cvt_pk_bf16_f32 v127, v54, v55
	v_cvt_pk_bf16_f32 v131, v46, v47
	v_mul_f32_e32 v44, 0x45800000, v32
	v_cndmask_b32_e32 v32, v32, v44, vcc
	v_mul_f32_e32 v32, 0x3e38aa3b, v32
	v_pk_mul_f32 v[30:31], v[32:33], v[30:31] op_sel_hi:[0,1]
	v_pk_mul_f32 v[26:27], v[32:33], v[26:27] op_sel_hi:[0,1]
	v_pk_mul_f32 v[30:31], v[30:31], v[188:189]
	v_pk_mul_f32 v[18:19], v[18:19], v[32:33] op_sel_hi:[1,0]
	v_pk_mul_f32 v[22:23], v[32:33], v[22:23] op_sel_hi:[0,1]
	v_pk_mul_f32 v[26:27], v[26:27], v[184:185]
	v_pk_mul_f32 v[18:19], v[18:19], v[34:35]
	v_pk_mul_f32 v[22:23], v[22:23], v[200:201]
	v_pk_mul_f32 v[34:35], v[142:143], v[30:31]
	v_pk_mul_f32 v[30:31], v[144:145], v[30:31]
	v_pk_mul_f32 v[48:49], v[68:69], v[32:33] op_sel_hi:[1,0]
	v_pk_fma_f32 v[34:35], v[144:145], v[26:27], v[34:35]
	v_pk_fma_f32 v[26:27], v[142:143], v[26:27], v[30:31] neg_lo:[0,0,1] neg_hi:[0,0,1]
	v_pk_mul_f32 v[30:31], v[146:147], v[22:23]
	v_pk_mul_f32 v[22:23], v[150:151], v[22:23]
	s_waitcnt vmcnt(5)
	v_pk_mul_f32 v[44:45], v[32:33], v[132:133] op_sel_hi:[0,1]
	s_waitcnt vmcnt(4)
	v_pk_mul_f32 v[46:47], v[32:33], v[72:73] op_sel_hi:[0,1]
	v_pk_mul_f32 v[40:41], v[48:49], v[40:41]
	v_pk_mul_f32 v[48:49], v[32:33], v[60:61] op_sel_hi:[0,1]
	v_pk_mul_f32 v[52:53], v[32:33], v[66:67] op_sel_hi:[0,1]
	v_pk_mul_f32 v[54:55], v[32:33], v[70:71] op_sel_hi:[0,1]
	v_pk_mul_f32 v[56:57], v[58:59], v[32:33] op_sel_hi:[1,0]
	v_pk_mul_f32 v[58:59], v[32:33], v[62:63] op_sel_hi:[0,1]
	v_pk_fma_f32 v[30:31], v[150:151], v[18:19], v[30:31]
	v_pk_fma_f32 v[18:19], v[146:147], v[18:19], v[22:23] neg_lo:[0,0,1] neg_hi:[0,0,1]
	v_pk_mul_f32 v[22:23], v[32:33], v[24:25] op_sel_hi:[0,1]
	v_pk_mul_f32 v[24:25], v[32:33], v[28:29] op_sel_hi:[0,1]
	v_pk_mul_f32 v[16:17], v[16:17], v[32:33] op_sel_hi:[1,0]
	v_pk_mul_f32 v[20:21], v[20:21], v[32:33] op_sel_hi:[1,0]
	v_mul_lo_u32 v33, v33, s60
	v_add3_u32 v173, v33, v86, 0
	s_waitcnt vmcnt(3)
	ds_write_b128 v173, v[0:3]
	s_waitcnt vmcnt(2)
	ds_write_b128 v173, v[4:7] offset:9216
	s_waitcnt vmcnt(1)
	ds_write_b128 v173, v[8:11] offset:18432
	s_waitcnt vmcnt(0)
	ds_write_b128 v173, v[12:15] offset:27648
	v_add_co_u32_e32 v0, vcc, s73, v64
	v_pk_mul_f32 v[54:55], v[54:55], v[186:187]
	s_nop 0
	v_addc_co_u32_e32 v1, vcc, 0, v65, vcc
	v_pk_mul_f32 v[52:53], v[52:53], v[182:183]
	v_pk_mul_f32 v[58:59], v[58:59], v[198:199]
	v_pk_mul_f32 v[60:61], v[134:135], v[54:55]
	v_pk_mul_f32 v[54:55], v[136:137], v[54:55]
	v_add_co_u32_e32 v2, vcc, s73, v82
	v_pk_mul_f32 v[56:57], v[56:57], v[196:197]
	v_pk_fma_f32 v[60:61], v[136:137], v[52:53], v[60:61]
	v_pk_fma_f32 v[52:53], v[134:135], v[52:53], v[54:55] neg_lo:[0,0,1] neg_hi:[0,0,1]
	v_pk_mul_f32 v[54:55], v[138:139], v[58:59]
	v_pk_mul_f32 v[58:59], v[140:141], v[58:59]
	v_addc_co_u32_e32 v3, vcc, 0, v83, vcc
	v_pk_fma_f32 v[54:55], v[140:141], v[56:57], v[54:55]
	v_pk_fma_f32 v[56:57], v[138:139], v[56:57], v[58:59] neg_lo:[0,0,1] neg_hi:[0,0,1]
	global_load_dwordx4 v[132:135], v[0:1], off
	global_load_dwordx4 v[136:139], v[2:3], off
	v_add_co_u32_e32 v0, vcc, s74, v64
	v_bfe_u32 v32, v229, 5, 1
	s_nop 0
	v_addc_co_u32_e32 v1, vcc, 0, v65, vcc
	v_add_co_u32_e32 v2, vcc, s74, v82
	v_lshlrev_b32_e32 v172, 4, v32
	s_nop 0
	v_addc_co_u32_e32 v3, vcc, 0, v83, vcc
	global_load_dwordx4 v[140:143], v[0:1], off
	global_load_dwordx4 v[144:147], v[2:3], off
	v_mul_u32_u24_e32 v0, 0x90, v227
	s_waitcnt lgkmcnt(0)
	s_barrier
; #define LAS __attribute__((address_space(3)))
; template <int MODE, bool FAST> __device__ __forceinline__ bool attn_unit(LAS unsigned char* lds, const AttU& U, const int wv) {
;     ...
;     f32x16 o[2][2];
; #pragma unroll
;     for (int a = 0; a < 2; ++a)
; #pragma unroll
;         for (int b = 0; b < 2; ++b)
; #pragma unroll
;             for (int r = 0; r < 16; ++r) o[a][b][r] = 0.f;
;     ...
;     pb[1][0] = (bf16x8){0, 0, 0, 0, 0, 0, 0, 0}; pb[1][1] = pb[1][0];
;     ATT_QK(0, 0, 0);
;     bf16x8 kpre[NPRE > 0 ? NPRE : 1];
; #pragma unroll
;     for (int i_ = 0; i_ < NPRE; ++i_) kpre[i_] = *(LAS const bf16x8*)(lds + koff + i_ * 32);
;     ...
;     if constexpr (FAST) {
;         for (int t2 = U.kt0; t2 < U.kt1; t2 += 2) { ATT_TILE(t2, 4, rk, rr, rv); ATT_TILE(t2 + 1, 4, rk2, rr2, rv2); }
	v_add3_u32 v184, v172, v0, 0
	v_cvt_pk_bf16_f32 v125, v80, v81
	ds_read_b128 v[80:83], v184
	ds_read_b128 v[108:111], v184 offset:32
	v_cvt_pk_bf16_f32 v121, v78, v79
	v_cvt_pk_bf16_f32 v124, v74, v75
	v_cvt_pk_bf16_f32 v128, v76, v77
	s_waitcnt lgkmcnt(1)
	v_mfma_f32_32x32x16_bf16 v[64:79], v[80:83], v[116:119], 0
	v_mul_f32_e64 v48, v48, v194
	v_mul_f32_e64 v49, v49, v195
	v_mul_f32_e64 v24, v24, v190
	v_mul_f32_e64 v25, v25, v191
	v_mul_f32_e64 v2, v104, v48
	v_mul_f32_e64 v3, v105, v49
	v_pk_mul_f32 v[4:5], v[106:107], v[48:49]
	v_pk_fma_f32 v[2:3], v[106:107], v[40:41], v[2:3] neg_lo:[0,0,1] neg_hi:[0,0,1]
	v_pk_fma_f32 v[4:5], v[104:105], v[40:41], v[4:5]
	ds_read_b128 v[104:107], v184 offset:64
	s_waitcnt lgkmcnt(1)
	v_mfma_f32_32x32x16_bf16 v[64:79], v[108:111], v[120:123], v[64:79]
	v_mul_f32_e64 v22, v22, v42
	v_mul_f32_e64 v23, v23, v43
	v_mul_f32_e64 v16, v16, v38
	v_mul_f32_e64 v17, v17, v39
	v_mul_f32_e64 v28, v152, v24
	v_mul_f32_e64 v29, v153, v25
	v_pk_mul_f32 v[24:25], v[154:155], v[24:25]
	v_pk_mul_f32 v[20:21], v[20:21], v[36:37]
	v_pk_fma_f32 v[28:29], v[154:155], v[22:23], v[28:29]
	v_pk_fma_f32 v[22:23], v[152:153], v[22:23], v[24:25] neg_lo:[0,0,1] neg_hi:[0,0,1]
	v_pk_mul_f32 v[24:25], v[156:157], v[16:17]
	v_cvt_pk_bf16_f32 v151, v2, v3
	v_pk_fma_f32 v[24:25], v[148:149], v[20:21], v[24:25]
	v_pk_mul_f32 v[20:21], v[156:157], v[20:21]
	v_cvt_pk_bf16_f32 v129, v84, v85
	v_pk_fma_f32 v[0:1], v[148:149], v[16:17], v[20:21] neg_lo:[0,0,1] neg_hi:[0,0,1]
	v_pk_mul_f32 v[46:47], v[46:47], v[180:181]
	v_cvt_pk_bf16_f32 v148, v0, v1
	ds_read_b128 v[0:3], v184 offset:96
	s_waitcnt lgkmcnt(1)
	v_mfma_f32_32x32x16_bf16 v[64:79], v[104:107], v[124:127], v[64:79]
	v_mul_f32_e64 v44, v44, v178
	v_mul_f32_e64 v45, v45, v179
	v_mul_f32_e64 v6, v92, v46
	v_mul_f32_e64 v7, v93, v47
	v_mul_f32_e64 v8, v94, v46
	v_mul_f32_e64 v9, v95, v47
	v_pk_fma_f32 v[6:7], v[94:95], v[44:45], v[6:7] neg_lo:[0,0,1] neg_hi:[0,0,1]
	v_pk_fma_f32 v[8:9], v[92:93], v[44:45], v[8:9]
	v_mov_b32_e32 v48, 0
	v_cvt_pk_bf16_f32 v149, v18, v19
	s_waitcnt lgkmcnt(0)
	v_mfma_f32_32x32x16_bf16 v[64:79], v[0:3], v[128:131], v[64:79]
	v_cvt_pk_bf16_f32 v150, v56, v57
	v_cvt_pk_bf16_f32 v152, v24, v25
	v_cvt_pk_bf16_f32 v153, v30, v31
	v_cvt_pk_bf16_f32 v154, v54, v55
	v_cvt_pk_bf16_f32 v155, v4, v5
	v_cvt_pk_bf16_f32 v156, v22, v23
	v_cvt_pk_bf16_f32 v157, v26, v27
	v_cvt_pk_bf16_f32 v158, v52, v53
	v_cvt_pk_bf16_f32 v159, v6, v7
	v_cvt_pk_bf16_f32 v160, v28, v29
	v_cvt_pk_bf16_f32 v161, v34, v35
	v_cvt_pk_bf16_f32 v162, v60, v61
	v_cvt_pk_bf16_f32 v163, v8, v9
	v_mov_b32_e32 v174, v168
	v_mov_b32_e32 v176, v50
	s_add_u32 s98, s46, s14
	s_addc_u32 s99, s47, s15
	s_add_u32 s98, s98, 0x12310000
	s_addc_u32 s99, s99, 0
	s_add_u32 s100, s46, s42
	s_addc_u32 s101, s47, s43
	s_add_u32 s100, s100, 0x12f10000
	s_addc_u32 s101, s101, 0
	s_mov_b64 s[42:43], 0
	v_mov_b32_e32 v96, 0
	v_mov_b32_e32 v97, 0
	v_mov_b32_e32 v98, 0
	v_mov_b32_e32 v99, 0
	v_mov_b32_e32 v100, 0
	v_mov_b32_e32 v101, 0
	v_mov_b32_e32 v102, 0
	v_mov_b32_e32 v103, 0
	v_mov_b32_e32 v49, v48
	v_mov_b32_e32 v50, v48
	v_mov_b32_e32 v51, v48
	v_mov_b32_e32 v52, v48
	v_mov_b32_e32 v53, v48
	v_mov_b32_e32 v54, v48
	v_mov_b32_e32 v55, v48
	v_mov_b32_e32 v56, v48
	v_mov_b32_e32 v57, v48
	v_mov_b32_e32 v58, v48
	v_mov_b32_e32 v59, v48
	v_mov_b32_e32 v60, v48
	v_mov_b32_e32 v61, v48
	v_mov_b32_e32 v62, v48
	v_mov_b32_e32 v63, v48
	v_mov_b32_e32 v32, v48
	v_mov_b32_e32 v33, v48
	v_mov_b32_e32 v34, v48
	v_mov_b32_e32 v35, v48
	v_mov_b32_e32 v36, v48
	v_mov_b32_e32 v37, v48
	v_mov_b32_e32 v38, v48
	v_mov_b32_e32 v39, v48
	v_mov_b32_e32 v40, v48
	v_mov_b32_e32 v41, v48
	v_mov_b32_e32 v42, v48
	v_mov_b32_e32 v43, v48
	v_mov_b32_e32 v44, v48
	v_mov_b32_e32 v45, v48
	v_mov_b32_e32 v46, v48
	v_mov_b32_e32 v47, v48
	v_mov_b32_e32 v16, v48
	v_mov_b32_e32 v17, v48
	v_mov_b32_e32 v18, v48
	v_mov_b32_e32 v19, v48
	v_mov_b32_e32 v20, v48
	v_mov_b32_e32 v21, v48
	v_mov_b32_e32 v22, v48
	v_mov_b32_e32 v23, v48
	v_mov_b32_e32 v24, v48
	v_mov_b32_e32 v25, v48
	v_mov_b32_e32 v26, v48
	v_mov_b32_e32 v27, v48
	v_mov_b32_e32 v28, v48
	v_mov_b32_e32 v29, v48
	v_mov_b32_e32 v30, v48
	v_mov_b32_e32 v31, v48
	v_mov_b32_e32 v0, v48
	v_mov_b32_e32 v1, v48
	v_mov_b32_e32 v2, v48
	v_mov_b32_e32 v3, v48
	v_mov_b32_e32 v4, v48
	v_mov_b32_e32 v5, v48
	v_mov_b32_e32 v6, v48
	v_mov_b32_e32 v7, v48
	v_mov_b32_e32 v8, v48
	v_mov_b32_e32 v9, v48
	v_mov_b32_e32 v10, v48
	v_mov_b32_e32 v11, v48
	v_mov_b32_e32 v12, v48
	v_mov_b32_e32 v13, v48
	v_mov_b32_e32 v14, v48
	v_mov_b32_e32 v15, v48
	v_mov_b32_e32 v178, v48
	v_mov_b32_e32 v179, v48
	s_waitcnt vmcnt(0)
.LBB0_437:
	s_add_i32 s14, s33, 2
	s_cmpk_gt_u32 s33, 0xfd
	s_cselect_b64 s[44:45], -1, 0
	s_and_b64 vcc, exec, s[44:45]
	s_cbranch_vccnz .LBB0_439
	s_and_b32 s4, s14, 2
	s_mulk_i32 s4, 0x4800
	v_add_u32_e32 v84, s4, v173
	s_waitcnt vmcnt(3)
	ds_write_b128 v84, v[132:135]
	s_waitcnt vmcnt(2)
	ds_write_b128 v84, v[136:139] offset:9216

;     ...
;     for (int qb = 0; qb < 2; ++qb) {
;         __builtin_amdgcn_sched_barrier(0);
;         const bf16_t* src = U.q + (size_t)(32 * qb + r32) * QP + 8 * hi;
;         u32x4 raw[ND];
; #pragma unroll
;         for (int d0 = 0; d0 < ND; ++d0) raw[d0] = *(const u32x4*)(src + 16 * d0);
;         int pos = U.tq0 + 32 * qb + r32; asm volatile("" : "+v"(pos));
;         if constexpr (MODE == 1) {
; #pragma unroll
;             for (int d0 = 0; d0 < ND; ++d0) qf[qb][d0] = __builtin_bit_cast(bf16x8, raw[d0]);
;         } else if constexpr (MODE == 0) {
;             float v[4][8]; float ss = 0.f;
; #pragma unroll
;             for (int d0 = 0; d0 < 4; ++d0)
; #pragma unroll
;                 for (int j = 0; j < 4; ++j) { const unsigned w = raw[d0][j]; v[d0][2 * j] = bflo(w); v[d0][2 * j + 1] = bfhi(w); ss += v[d0][2 * j] * v[d0][2 * j] + v[d0][2 * j + 1] * v[d0][2 * j + 1]; }
;             ss = pairsum(ss);
;             const float rstd = rsqrtf(ss * (1.0f / 64.0f) + EPSN) * C2_64;
; #pragma unroll
;             for (int d0 = 0; d0 < 4; ++d0)
; #pragma unroll
;                 for (int j = 0; j < 8; ++j) v[d0][j] *= rstd * U.gain[16 * d0 + 8 * hi + j];
;             const int row = pos >> 6, col = pos & 63;
; #pragma unroll
;             for (int j = 0; j < 8; ++j) {
;                 __builtin_amdgcn_sched_barrier(0);
;                 const float fi = hi ? invf_c(8 + j) : invf_c(j); float c, s;
;                 rope_cs(row, fi, c, s); { const float x1 = v[0][j], x2 = v[1][j]; v[0][j] = x1 * c - x2 * s; v[1][j] = x2 * c + x1 * s; }
;                 rope_cs(col, fi, c, s); { const float x1 = v[2][j], x2 = v[3][j]; v[2][j] = x1 * c - x2 * s; v[3][j] = x2 * c + x1 * s; }
;             }
; #pragma unroll
;             for (int d0 = 0; d0 < 4; ++d0) { u32x4 w; w.x = pk(v[d0][0], v[d0][1]); w.y = pk(v[d0][2], v[d0][3]); w.z = pk(v[d0][4], v[d0][5]); w.w = pk(v[d0][6], v[d0][7]); qf[qb][d0] = __builtin_bit_cast(bf16x8, w); }
;         } else {
; #pragma unroll
;             for (int d0 = 0; d0 < 4; ++d0) qf[qb][d0] = __builtin_bit_cast(bf16x8, raw[d0]);
;             float a[8], b[8];
; #pragma unroll
;             for (int j = 0; j < 4; ++j) { a[2 * j] = bflo(raw[ND - 2][j]); a[2 * j + 1] = bfhi(raw[ND - 2][j]); b[2 * j] = bflo(raw[ND - 1][j]); b[2 * j + 1] = bfhi(raw[ND - 1][j]); }
; #pragma unroll
.LBB0_922:
	s_lshr_b64 s[6:7], s[20:21], 4
	s_lshl_b64 s[8:9], s[6:7], 25
	s_add_u32 s40, s18, s8
	s_addc_u32 s41, s19, s9
	s_add_i32 s9, s59, s50
	s_and_b32 s44, s58, 15
	s_lshr_b32 s8, s9, 4
	s_and_b32 s24, s9, 15
	s_mov_b32 s9, s31
	s_lshl_b32 s30, s44, 13
	s_lshl_b64 s[6:7], s[6:7], 20
	s_lshl_b64 s[10:11], s[8:9], 14
	s_add_u32 s22, s10, s63
	s_addc_u32 s23, s11, s66
	s_mul_i32 s10, s23, 0xc00
	s_mul_hi_u32 s11, s22, 0xc00
	s_add_i32 s11, s11, s10
	s_mul_i32 s10, s22, 0xc00
	s_add_u32 s10, s26, s10
	s_addc_u32 s11, s27, s11
	s_mul_i32 s12, s24, 0xc0
	s_add_u32 s42, s10, s12
	s_addc_u32 s43, s11, 0
	s_lshl_b64 s[12:13], s[8:9], 25
	s_add_u32 s10, s33, s12
	s_addc_u32 s11, s37, s13
	s_lshl_b32 s60, s24, 6
	s_lshl_b32 s35, s24, 7
	s_add_u32 s10, s10, s35
	s_addc_u32 s11, s11, 0
	s_lshl_b64 s[8:9], s[8:9], 20
	s_add_u32 s8, s25, s8
	s_addc_u32 s9, s52, s9
	s_add_u32 s12, s46, s12
	s_addc_u32 s13, s47, s13
	s_lshl_b32 s24, s24, 13
	s_add_u32 s12, s12, s24
	v_mbcnt_lo_u32_b32 v8, -1, 0
	v_mbcnt_hi_u32_b32 v8, -1, v8
	s_addc_u32 s13, s13, 0
	v_and_b32_e32 v237, 63, v8
	v_and_b32_e32 v187, 31, v8
	v_cmp_gt_u32_e32 vcc, 32, v237
	v_mul_u32_u24_e32 v0, 0x600, v187
	v_lshlrev_b32_e32 v96, 1, v0
	v_lshrrev_b32_e32 v2, 1, v8
	v_lshl_add_u64 v[0:1], s[42:43], 0, v[96:97]
	v_and_b32_e32 v96, 16, v2
	v_lshl_add_u64 v[10:11], v[0:1], 0, v[96:97]
	global_load_dwordx4 v[0:3], v[10:11], off offset:128
	global_load_dwordx4 v[4:7], v[10:11], off offset:160
	global_load_dwordx4 v[98:101], v[10:11], off
	global_load_dwordx4 v[102:105], v[10:11], off offset:32
	global_load_dwordx4 v[106:109], v[10:11], off offset:64
	global_load_dwordx4 v[110:113], v[10:11], off offset:96
	v_or_b32_e32 v9, s63, v187
	s_waitcnt vmcnt(5)
	v_and_b32_e32 v18, 0xffff0000, v0
	v_cvt_f32_i32_e32 v9, v9
	s_waitcnt vmcnt(4)
	v_and_b32_e32 v19, 0xffff0000, v4
	v_and_b32_e32 v20, 0xffff0000, v1
	v_and_b32_e32 v21, 0xffff0000, v5
	v_and_b32_e32 v22, 0xffff0000, v2
	v_and_b32_e32 v23, 0xffff0000, v6
	v_and_b32_e32 v24, 0xffff0000, v3
	v_and_b32_e32 v25, 0xffff0000, v7
	v_mov_b32_e32 v10, 0x3c23d70a
	v_cndmask_b32_e64 v27, v10, 1.0, vcc
	v_mul_f32_e32 v10, v27, v9
	v_mul_f32_e32 v11, 0.15915494, v10
	v_rndne_f32_e32 v11, v11
	v_fmac_f32_e32 v10, 0xc0c90fdb, v11
	v_fmac_f32_e32 v10, 0x343bbd2e, v11
	v_mul_f32_e32 v11, 0.15915494, v10
	v_sin_f32_e32 v10, v11
	v_cos_f32_e32 v11, v11
	v_lshlrev_b32_e32 v13, 16, v0
	v_lshlrev_b32_e32 v12, 16, v4
	v_mov_b32_e32 v17, v10
	v_mov_b32_e32 v16, v11
	v_pk_mul_f32 v[14:15], v[10:11], v[12:13]
	v_pk_mul_f32 v[10:11], v[16:17], v[12:13]
	v_mov_b32_e32 v0, 0x3bb8449c
	v_mov_b32_e32 v4, 0x3f0ff59a
	v_cndmask_b32_e32 v29, v0, v4, vcc
	v_mul_f32_e32 v0, v29, v9
	v_mul_f32_e32 v4, 0.15915494, v0
	v_rndne_f32_e32 v4, v4
	v_fmac_f32_e32 v0, 0xc0c90fdb, v4
	v_fmac_f32_e32 v0, 0x343bbd2e, v4
	v_mul_f32_e32 v0, 0.15915494, v0
	v_cos_f32_e32 v4, v0
	v_sin_f32_e32 v0, v0
	v_mov_b32_e32 v12, v15
	v_mov_b32_e32 v16, v11
	v_mul_f32_e32 v13, v4, v18
	v_mul_f32_e32 v15, v0, v19
	v_pk_add_f32 v[12:13], v[12:13], v[14:15] neg_lo:[0,1] neg_hi:[0,1]
	v_mul_f32_e32 v15, v4, v19
	v_mul_f32_e32 v17, v0, v18
	v_mov_b32_e32 v14, v10
	v_pk_add_f32 v[10:11], v[14:15], v[16:17]
	v_mov_b32_e32 v0, 0x3b4f3e37
	v_mov_b32_e32 v4, 0x3ea1e89b
	v_cndmask_b32_e32 v47, v0, v4, vcc
	v_mul_f32_e32 v0, v47, v9
	v_mul_f32_e32 v4, 0.15915494, v0
	v_rndne_f32_e32 v4, v4
	v_fmac_f32_e32 v0, 0xc0c90fdb, v4
	v_fmac_f32_e32 v0, 0x343bbd2e, v4
	v_mul_f32_e32 v0, 0.15915494, v0
	v_sin_f32_e32 v14, v0
	v_cos_f32_e32 v15, v0
	v_lshlrev_b32_e32 v1, 16, v1
	v_lshlrev_b32_e32 v0, 16, v5
	v_mov_b32_e32 v17, v14
	v_mov_b32_e32 v16, v15
	v_pk_mul_f32 v[4:5], v[14:15], v[0:1]
	v_pk_mul_f32 v[0:1], v[16:17], v[0:1]
	v_mov_b32_e32 v14, 0x3ae91528
	v_mov_b32_e32 v15, 0x3e361887
	v_cndmask_b32_e32 v53, v14, v15, vcc
	v_mul_f32_e32 v14, v53, v9
	v_mul_f32_e32 v15, 0.15915494, v14
	v_rndne_f32_e32 v15, v15
	v_fmac_f32_e32 v14, 0xc0c90fdb, v15
	v_fmac_f32_e32 v14, 0x343bbd2e, v15
	v_mul_f32_e32 v14, 0.15915494, v14
	v_cos_f32_e32 v16, v14
	v_sin_f32_e32 v17, v14
	v_mov_b32_e32 v14, v5
	v_mul_f32_e32 v15, v16, v20
	v_mul_f32_e32 v5, v17, v21
	v_pk_add_f32 v[4:5], v[14:15], v[4:5] neg_lo:[0,1] neg_hi:[0,1]
	v_mul_f32_e32 v15, v16, v21
	v_mul_f32_e32 v17, v17, v20
	v_mov_b32_e32 v14, v0
	v_mov_b32_e32 v16, v1
	v_pk_add_f32 v[0:1], v[14:15], v[16:17]
	v_mov_b32_e32 v14, 0x3a83126f
	v_mov_b32_e32 v15, 0x3dcccccd
	v_cndmask_b32_e32 v56, v14, v15, vcc
	v_mul_f32_e32 v14, v56, v9
	v_mul_f32_e32 v15, 0.15915494, v14
	v_rndne_f32_e32 v15, v15
	v_fmac_f32_e32 v14, 0xc0c90fdb, v15
	v_fmac_f32_e32 v14, 0x343bbd2e, v15
	v_mul_f32_e32 v15, 0.15915494, v14
	v_sin_f32_e32 v14, v15
	v_cos_f32_e32 v15, v15
	v_lshlrev_b32_e32 v17, 16, v2
	v_lshlrev_b32_e32 v16, 16, v6
	v_mov_b32_e32 v21, v14
	v_mov_b32_e32 v20, v15
	v_pk_mul_f32 v[18:19], v[14:15], v[16:17]
	v_pk_mul_f32 v[14:15], v[20:21], v[16:17]
	v_mov_b32_e32 v2, 0x3d6655c3
	v_cndmask_b32_e32 v57, v193, v2, vcc
	v_mul_f32_e32 v2, v57, v9
	v_mul_f32_e32 v6, 0.15915494, v2
	v_rndne_f32_e32 v6, v6
	v_fmac_f32_e32 v2, 0xc0c90fdb, v6
	v_fmac_f32_e32 v2, 0x343bbd2e, v6
	v_mul_f32_e32 v2, 0.15915494, v2
	v_cos_f32_e32 v6, v2
	v_sin_f32_e32 v2, v2
	v_mov_b32_e32 v16, v19
	v_mov_b32_e32 v20, v15
	v_mul_f32_e32 v17, v6, v22
	v_mul_f32_e32 v19, v2, v23
	v_pk_add_f32 v[16:17], v[16:17], v[18:19] neg_lo:[0,1] neg_hi:[0,1]
	v_mul_f32_e32 v19, v6, v23
	v_mul_f32_e32 v21, v2, v22
	v_mov_b32_e32 v18, v14
	v_pk_add_f32 v[14:15], v[18:19], v[20:21]
	v_mov_b32_e32 v2, 0x39a5cb5f
	v_mov_b32_e32 v6, 0x3d0186e2
	v_cndmask_b32_e32 v22, v2, v6, vcc
	v_mul_f32_e32 v2, v22, v9
	v_mul_f32_e32 v6, 0.15915494, v2
; __device__ __forceinline__ unsigned pk(float lo, float hi) { f32x2_t v = {lo, hi}; bf16x2_t b = __builtin_convertvector(v, bf16x2_t); return __builtin_bit_cast(unsigned, b); }
; #define BAR_LDS() asm volatile("s_waitcnt lgkmcnt(0)\n\ts_barrier" ::: "memory")
; #define ATT_LOADS(RK, RR, RV, tt) do { RK = *(const u32x4*)((const char*)(U.k + (size_t)(tt) * 64 * KP) + kgo); if (MODE == 2) RR = *(const u32x2*)((const char*)(U.kr + (size_t)(tt) * 64 * 32) + krgo); \
;         RV = *(const u32x4*)((const char*)(U.vt + (size_t)(tt) * VTS) + vgo); } while (0)
; #define ATT_LOAD(tt) ATT_LOADS(rk, rr, rv, tt)
; #define ATT_STORE(ss) ATT_STORES(rk, rr, rv, ss)
;     ...
;             for (int j = 0; j < 8; ++j) { __builtin_amdgcn_sched_barrier(0); const float fi = hi ? invf_c(8 + j) : invf_c(j); float c, s; rope_cs(pos, fi, c, s);
;                 const float x1 = a[j], x2 = b[j]; a[j] = x1 * c - x2 * s; b[j] = x2 * c + x1 * s; }
;             u32x4 wa, wb; wa.x = pk(a[0], a[1]); wa.y = pk(a[2], a[3]); wa.z = pk(a[4], a[5]); wa.w = pk(a[6], a[7]); wb.x = pk(b[0], b[1]); wb.y = pk(b[2], b[3]); wb.z = pk(b[4], b[5]); wb.w = pk(b[6], b[7]);
;             qf[qb][ND - 2] = __builtin_bit_cast(bf16x8, wa); qf[qb][ND - 1] = __builtin_bit_cast(bf16x8, wb);
; template <int MODE, bool FAST> __device__ __forceinline__ bool attn_unit(LAS unsigned char* lds, const AttU& U, const int wv) {
;     ...
;     const int krow = tid >> 3, kc = tid & 7;
;     const unsigned kgo = (unsigned)(krow * KP + kc * 8) * 2u, krgo = (unsigned)(krow * 32 + kc * 4) * 2u, vgo = (unsigned)tid * 16u;
;     const unsigned kdst = krow * KSTR + kc * 16, krdst = krow * KSTR + 128 + kc * 8, vdst = 64 * KSTR + krow * VSTR + kc * 16;
;     u32x4 rk, rv, rk2, rv2; u32x2 rr = {0u, 0u}, rr2 = {0u, 0u};
;     ...
;     const int NT = U.kt1 - U.kt0;
;     ATT_LOAD(U.kt0); ATT_STORE(0);
;     if (NT > 1) { ATT_LOAD(U.kt0 + 1); ATT_STORE(1); }
;     if (NT > 2) ATT_LOAD(U.kt0 + 2);
;     if constexpr (FAST) { if (NT > 3) ATT_LOADS(rk2, rr2, rv2, U.kt0 + 3); }
;     BAR_LDS();
	v_rndne_f32_e32 v6, v6
	v_fmac_f32_e32 v2, 0xc0c90fdb, v6
	v_fmac_f32_e32 v2, 0x343bbd2e, v6
	v_mul_f32_e32 v2, 0.15915494, v2
	v_sin_f32_e32 v18, v2
	v_cos_f32_e32 v19, v2
	v_lshlrev_b32_e32 v3, 16, v3
	v_lshlrev_b32_e32 v2, 16, v7
	v_mov_b32_e32 v21, v18
	v_mov_b32_e32 v20, v19
	v_pk_mul_f32 v[6:7], v[18:19], v[2:3]
	v_pk_mul_f32 v[2:3], v[20:21], v[2:3]
	v_cndmask_b32_e32 v86, v234, v235, vcc
	v_mul_f32_e32 v9, v86, v9
	v_mul_f32_e32 v18, 0.15915494, v9
	v_rndne_f32_e32 v18, v18
	v_fmac_f32_e32 v9, 0xc0c90fdb, v18
	v_fmac_f32_e32 v9, 0x343bbd2e, v18
	v_mul_f32_e32 v9, 0.15915494, v9
	v_cos_f32_e32 v20, v9
	v_sin_f32_e32 v9, v9
	v_mov_b32_e32 v18, v7
	v_cvt_pk_bf16_f32 v114, v12, v13
	v_mul_f32_e32 v19, v20, v24
	v_mul_f32_e32 v7, v9, v25
	v_pk_add_f32 v[6:7], v[18:19], v[6:7] neg_lo:[0,1] neg_hi:[0,1]
	v_mul_f32_e32 v19, v20, v25
	v_mul_f32_e32 v21, v9, v24
	v_mov_b32_e32 v18, v2
	v_mov_b32_e32 v20, v3
	v_pk_add_f32 v[2:3], v[18:19], v[20:21]
	v_cvt_pk_bf16_f32 v115, v4, v5
	v_cvt_pk_bf16_f32 v116, v16, v17
	v_cvt_pk_bf16_f32 v117, v6, v7
	v_cvt_pk_bf16_f32 v118, v10, v11
	v_cvt_pk_bf16_f32 v119, v0, v1
	v_cvt_pk_bf16_f32 v120, v14, v15
	v_cvt_pk_bf16_f32 v121, v2, v3
	v_or_b32_e32 v9, 32, v237
	v_mul_u32_u24_e32 v0, 0x600, v9
	v_lshlrev_b32_e32 v0, 1, v0
	v_mov_b32_e32 v1, v97
	v_lshl_add_u64 v[0:1], s[42:43], 0, v[0:1]
	v_lshl_add_u64 v[4:5], v[0:1], 0, v[96:97]
	global_load_dwordx4 v[122:125], v[4:5], off
	global_load_dwordx4 v[126:129], v[4:5], off offset:32
	global_load_dwordx4 v[130:133], v[4:5], off offset:64
	global_load_dwordx4 v[134:137], v[4:5], off offset:96
	global_load_dwordx4 v[0:3], v[4:5], off offset:128
	s_nop 0
	global_load_dwordx4 v[4:7], v[4:5], off offset:160
	v_or_b32_e32 v9, s63, v9
	s_nop 0
	v_cvt_f32_i32_e32 v87, v9
	v_add_u32_e32 v9, s36, v8
	v_and_b32_e32 v10, 7, v8
	v_ashrrev_i32_e32 v88, 3, v9
	v_lshlrev_b32_e32 v28, 4, v10
	v_mul_f32_e32 v11, v22, v87
	v_lshl_or_b32 v96, v88, 11, v28
	v_mul_f32_e32 v12, 0.15915494, v11
	v_lshlrev_b32_e32 v89, 3, v10
	v_lshlrev_b32_e32 v66, 6, v88
	v_lshl_add_u64 v[34:35], s[10:11], 0, v[96:97]
	v_rndne_f32_e32 v12, v12
	v_or_b32_e32 v30, v66, v89
	v_mov_b32_e32 v31, v97
	v_add_co_u32_e32 v18, vcc, s39, v34
	v_fmac_f32_e32 v11, 0xc0c90fdb, v12
	v_lshl_add_u64 v[36:37], s[8:9], 0, v[30:31]
	v_addc_co_u32_e32 v19, vcc, 0, v35, vcc
	v_fmac_f32_e32 v11, 0x343bbd2e, v12
	v_lshlrev_b32_e32 v32, 4, v9
	v_mov_b32_e32 v33, v97
	v_add_co_u32_e32 v40, vcc, s92, v36
	v_mul_f32_e32 v46, 0.15915494, v11
	global_load_dwordx4 v[10:13], v96, s[10:11]
	global_load_dwordx4 v[14:17], v32, s[12:13]
	v_lshl_add_u64 v[38:39], s[12:13], 0, v[32:33]
	global_load_dwordx4 v[18:21], v[18:19], off
	v_addc_co_u32_e32 v41, vcc, 0, v37, vcc
	global_load_dwordx2 v[42:43], v30, s[8:9]
	global_load_dwordx2 v[44:45], v[40:41], off offset:-4096
	v_add_co_u32_e32 v22, vcc, s39, v38
	v_mul_f32_e32 v9, v27, v87
	s_nop 0
	v_addc_co_u32_e32 v23, vcc, 0, v39, vcc
	global_load_dwordx4 v[22:25], v[22:23], off
	v_mul_f32_e32 v27, 0.15915494, v9
	v_rndne_f32_e32 v27, v27
	v_fmac_f32_e32 v9, 0xc0c90fdb, v27
	v_fmac_f32_e32 v9, 0x343bbd2e, v27
	v_mul_f32_e32 v9, 0.15915494, v9
	v_cos_f32_e32 v48, v9
	v_sin_f32_e32 v50, v9
	v_mul_f32_e32 v9, v29, v87
	v_mul_f32_e32 v27, 0.15915494, v9
	v_rndne_f32_e32 v27, v27
	v_fmac_f32_e32 v9, 0xc0c90fdb, v27
	v_fmac_f32_e32 v9, 0x343bbd2e, v27
	v_mul_f32_e32 v9, 0.15915494, v9
	v_cos_f32_e32 v49, v9
	v_sin_f32_e32 v51, v9
	v_mul_f32_e32 v9, v47, v87
	v_mul_f32_e32 v27, 0.15915494, v9
	v_rndne_f32_e32 v27, v27
	v_fmac_f32_e32 v9, 0xc0c90fdb, v27
	v_fmac_f32_e32 v9, 0x343bbd2e, v27
	v_mul_f32_e32 v9, 0.15915494, v9
	v_cos_f32_e32 v52, v9
	v_sin_f32_e32 v54, v9
	v_mul_f32_e32 v9, v53, v87
	v_mul_f32_e32 v27, 0.15915494, v9
	v_rndne_f32_e32 v27, v27
	v_fmac_f32_e32 v9, 0xc0c90fdb, v27
	v_fmac_f32_e32 v9, 0x343bbd2e, v27
	v_mul_f32_e32 v9, 0.15915494, v9
	v_cos_f32_e32 v53, v9
	v_sin_f32_e32 v55, v9
	v_mul_f32_e32 v9, v56, v87
	v_mul_f32_e32 v27, 0.15915494, v9
	v_rndne_f32_e32 v27, v27
	v_fmac_f32_e32 v9, 0xc0c90fdb, v27
	v_fmac_f32_e32 v9, 0x343bbd2e, v27
	v_mul_f32_e32 v9, 0.15915494, v9
	v_cos_f32_e32 v56, v9
	v_sin_f32_e32 v58, v9
	v_mul_f32_e32 v9, v57, v87
	v_mul_f32_e32 v27, 0.15915494, v9
	v_rndne_f32_e32 v27, v27
	v_fmac_f32_e32 v9, 0xc0c90fdb, v27
	v_fmac_f32_e32 v9, 0x343bbd2e, v27
	v_mul_lo_u32 v29, v88, s5
	s_mov_b32 s8, 0x60000
	v_mul_f32_e32 v9, 0.15915494, v9
	v_bfe_u32 v27, v8, 5, 1
	v_add_u32_e32 v238, v29, v28
	v_add_co_u32_e32 v8, vcc, s8, v38
	v_cos_f32_e32 v57, v9
	v_sin_f32_e32 v59, v9
	v_addc_co_u32_e32 v9, vcc, 0, v39, vcc
	v_sub_u32_e32 v239, v238, v89
	v_sub_u32_e32 v240, v238, v66
	v_add_u32_e32 v47, 0, v238
	global_load_dwordx4 v[138:141], v[8:9], off
	v_add_u32_e32 v8, 0, v239
	v_add_u32_e32 v9, 0, v240
	global_load_dwordx2 v[188:189], v[40:41], off
	v_lshlrev_b32_e32 v186, 4, v27
	v_mad_u32_u24 v241, v187, s5, v186
	v_add_u32_e32 v242, 0, v241
	s_waitcnt vmcnt(9)
	v_lshlrev_b32_e32 v62, 16, v0
	v_and_b32_e32 v63, 0xffff0000, v0
	s_waitcnt vmcnt(7)
	ds_write_b128 v47, v[10:13]
	v_lshlrev_b32_e32 v60, 16, v4
	v_and_b32_e32 v61, 0xffff0000, v4
	v_pk_mul_f32 v[64:65], v[50:51], v[62:63]
	v_lshlrev_b32_e32 v0, 16, v1
	s_waitcnt vmcnt(4)
	ds_write_b64 v8, v[42:43] offset:128
	ds_write_b128 v9, v[14:17] offset:13312
	ds_write_b128 v47, v[18:21] offset:22528
	s_waitcnt vmcnt(3)
	ds_write_b64 v8, v[44:45] offset:22656
	s_waitcnt vmcnt(2)
	ds_write_b128 v9, v[22:25] offset:35840
	v_add_co_u32_e32 v8, vcc, s4, v34
	v_pk_fma_f32 v[84:85], v[48:49], v[60:61], v[64:65]
	s_nop 0
	v_addc_co_u32_e32 v9, vcc, 0, v35, vcc
	v_add_co_u32_e32 v10, vcc, s4, v38
	v_and_b32_e32 v1, 0xffff0000, v1
	s_nop 0
	v_addc_co_u32_e32 v11, vcc, 0, v39, vcc
	global_load_dwordx4 v[142:145], v[8:9], off
	global_load_dwordx4 v[146:149], v[10:11], off
	v_add_co_u32_e32 v8, vcc, s8, v34
	s_movk_i32 s8, 0x3000
	s_nop 0
	v_addc_co_u32_e32 v9, vcc, 0, v35, vcc
	global_load_dwordx4 v[150:153], v[8:9], off
	v_add_co_u32_e32 v8, vcc, s8, v36
	v_lshlrev_b32_e32 v4, 16, v5
	s_nop 0
	v_addc_co_u32_e32 v9, vcc, 0, v37, vcc
	global_load_dwordx2 v[190:191], v[8:9], off
	s_waitcnt lgkmcnt(0)
	s_barrier
; #define LAS __attribute__((address_space(3)))
; __device__ __forceinline__ unsigned pk(float lo, float hi) { f32x2_t v = {lo, hi}; bf16x2_t b = __builtin_convertvector(v, bf16x2_t); return __builtin_bit_cast(unsigned, b); }
;     ...
;             for (int j = 0; j < 8; ++j) { __builtin_amdgcn_sched_barrier(0); const float fi = hi ? invf_c(8 + j) : invf_c(j); float c, s; rope_cs(pos, fi, c, s);
;                 const float x1 = a[j], x2 = b[j]; a[j] = x1 * c - x2 * s; b[j] = x2 * c + x1 * s; }
;             u32x4 wa, wb; wa.x = pk(a[0], a[1]); wa.y = pk(a[2], a[3]); wa.z = pk(a[4], a[5]); wa.w = pk(a[6], a[7]); wb.x = pk(b[0], b[1]); wb.y = pk(b[2], b[3]); wb.z = pk(b[4], b[5]); wb.w = pk(b[6], b[7]);
;             qf[qb][ND - 2] = __builtin_bit_cast(bf16x8, wa); qf[qb][ND - 1] = __builtin_bit_cast(bf16x8, wb);
; template <int MODE, bool FAST> __device__ __forceinline__ bool attn_unit(LAS unsigned char* lds, const AttU& U, const int wv) {
;     ...
;     pb[1][0] = (bf16x8){0, 0, 0, 0, 0, 0, 0, 0}; pb[1][1] = pb[1][0];
;     ATT_QK(0, 0, 0);
;     bf16x8 kpre[NPRE > 0 ? NPRE : 1];
; #pragma unroll
;     for (int i_ = 0; i_ < NPRE; ++i_) kpre[i_] = *(LAS const bf16x8*)(lds + koff + i_ * 32);
;     ...
;     if constexpr (FAST) {
;         for (int t2 = U.kt0; t2 < U.kt1; t2 += 2) { ATT_TILE(t2, 4, rk, rr, rv); ATT_TILE(t2 + 1, 4, rk2, rr2, rv2); }
	ds_read_b128 v[80:83], v242
	ds_read_b128 v[174:177], v242 offset:32
	s_waitcnt lgkmcnt(1)
	v_mfma_f32_32x32x16_bf16 v[64:79], v[80:83], v[98:101], 0
	ds_read_b128 v[170:173], v242 offset:64
	v_and_b32_e32 v5, 0xffff0000, v5
	v_mul_f32_e64 v8, v54, v0
	v_mul_f32_e64 v9, v55, v1
	v_lshlrev_b32_e32 v18, 16, v3
	v_pk_fma_f32 v[12:13], v[52:53], v[4:5], v[8:9]
	v_pk_mul_f32 v[4:5], v[54:55], v[4:5]
	v_lshlrev_b32_e32 v8, 16, v2
	s_waitcnt lgkmcnt(1)
	v_mfma_f32_32x32x16_bf16 v[64:79], v[174:177], v[102:105], v[64:79]
	v_and_b32_e32 v9, 0xffff0000, v2
	v_fma_f32 v4, v52, v0, -v4
	v_fma_f32 v5, v53, v1, -v5
	v_lshlrev_b32_e32 v0, 16, v6
	v_and_b32_e32 v1, 0xffff0000, v6
	v_pk_mul_f32 v[10:11], v[58:59], v[8:9]
	v_and_b32_e32 v19, 0xffff0000, v3
	v_pk_fma_f32 v[14:15], v[56:57], v[0:1], v[10:11]
	v_pk_mul_f32 v[0:1], v[58:59], v[0:1]
	v_cos_f32_e32 v26, v46
	v_pk_fma_f32 v[16:17], v[56:57], v[8:9], v[0:1] neg_lo:[0,0,1] neg_hi:[0,0,1]
	ds_read_b128 v[8:11], v242 offset:96
	s_waitcnt lgkmcnt(1)
	v_mfma_f32_32x32x16_bf16 v[64:79], v[170:173], v[106:109], v[64:79]
	v_mul_f32_e32 v0, v86, v87
	v_mul_f32_e32 v1, 0.15915494, v0
	v_rndne_f32_e32 v1, v1
	v_fmac_f32_e32 v0, 0xc0c90fdb, v1
	v_fmac_f32_e32 v0, 0x343bbd2e, v1
	v_mul_f32_e32 v0, 0.15915494, v0
	v_sin_f32_e32 v47, v0
	v_cos_f32_e32 v27, v0
	ds_read_b128 v[0:3], v242 offset:128
	s_waitcnt lgkmcnt(1)
	v_mfma_f32_32x32x16_bf16 v[64:79], v[8:11], v[110:113], v[64:79]
	v_sin_f32_e32 v46, v46
	v_lshlrev_b32_e32 v6, 16, v7
	v_and_b32_e32 v7, 0xffff0000, v7
	v_cvt_pk_bf16_f32 v155, v4, v5
	v_pk_mul_f32 v[8:9], v[46:47], v[18:19]
	v_pk_mul_f32 v[50:51], v[50:51], v[60:61]
	v_pk_fma_f32 v[8:9], v[26:27], v[6:7], v[8:9]
	v_pk_mul_f32 v[6:7], v[46:47], v[6:7]
	v_pk_fma_f32 v[48:49], v[48:49], v[62:63], v[50:51] neg_lo:[0,0,1] neg_hi:[0,0,1]
	v_pk_fma_f32 v[10:11], v[26:27], v[18:19], v[6:7] neg_lo:[0,0,1] neg_hi:[0,0,1]
	ds_read_b128 v[4:7], v242 offset:160
	s_waitcnt lgkmcnt(1)
	v_mfma_f32_32x32x16_bf16 v[64:79], v[0:3], v[114:117], v[64:79]
	v_lshlrev_b32_e32 v0, 6, v187
	s_add_u32 s6, s56, s6
	v_cvt_pk_bf16_f32 v154, v48, v49
	v_sub_u32_e32 v243, v241, v0
	s_addc_u32 s7, s57, s7
	v_mov_b32_e32 v48, 0
	v_cvt_pk_bf16_f32 v156, v16, v17
	s_waitcnt lgkmcnt(0)
	v_mfma_f32_32x32x16_bf16 v[64:79], v[4:7], v[118:121], v[64:79]
	v_cvt_pk_bf16_f32 v157, v10, v11
	v_cvt_pk_bf16_f32 v158, v84, v85
	v_cvt_pk_bf16_f32 v159, v12, v13
	v_cvt_pk_bf16_f32 v160, v14, v15
	v_cvt_pk_bf16_f32 v161, v8, v9
	v_add_u32_e32 v244, 0, v243
	v_add_u32_e32 v245, v89, v29
	v_mad_u64_u32 v[198:199], s[8:9], v88, s69, v[28:29]
	v_lshl_or_b32 v96, s44, 7, v96
	v_mov_b32_e32 v200, v32
	s_add_u32 s98, s40, 0x12380000
	s_addc_u32 s99, s41, 0
	s_add_u32 s100, s40, s30
	s_addc_u32 s101, s41, s31
	s_add_u32 s100, s100, 0x18380000
	s_addc_u32 s101, s101, 0
	v_lshl_add_u64 v[202:203], s[6:7], 0, v[30:31]
	s_mov_b64 s[42:43], 0
	v_mov_b32_e32 v162, 0
	v_mov_b32_e32 v163, 0
	v_mov_b32_e32 v164, 0
	v_mov_b32_e32 v165, 0
	v_mov_b32_e32 v166, 0
	v_mov_b32_e32 v167, 0
	v_mov_b32_e32 v168, 0
	v_mov_b32_e32 v169, 0
	s_mov_b32 s61, 0
	v_mov_b32_e32 v49, v48
	v_mov_b32_e32 v50, v48
	v_mov_b32_e32 v51, v48
	v_mov_b32_e32 v52, v48
	v_mov_b32_e32 v53, v48
	v_mov_b32_e32 v54, v48
	v_mov_b32_e32 v55, v48
	v_mov_b32_e32 v56, v48
	v_mov_b32_e32 v57, v48
	v_mov_b32_e32 v58, v48
	v_mov_b32_e32 v59, v48
	v_mov_b32_e32 v60, v48
	v_mov_b32_e32 v61, v48
	v_mov_b32_e32 v62, v48
	v_mov_b32_e32 v63, v48
	v_mov_b32_e32 v32, v48
	v_mov_b32_e32 v33, v48
	v_mov_b32_e32 v34, v48
	v_mov_b32_e32 v35, v48
	v_mov_b32_e32 v36, v48
	v_mov_b32_e32 v37, v48
	v_mov_b32_e32 v38, v48
	v_mov_b32_e32 v39, v48
	v_mov_b32_e32 v40, v48
	v_mov_b32_e32 v41, v48
	v_mov_b32_e32 v42, v48
	v_mov_b32_e32 v43, v48
	v_mov_b32_e32 v44, v48
	v_mov_b32_e32 v45, v48
	v_mov_b32_e32 v46, v48
	v_mov_b32_e32 v47, v48
	v_mov_b32_e32 v16, v48
	v_mov_b32_e32 v17, v48
	v_mov_b32_e32 v18, v48
	v_mov_b32_e32 v19, v48
	v_mov_b32_e32 v20, v48
	v_mov_b32_e32 v21, v48
	v_mov_b32_e32 v22, v48
	v_mov_b32_e32 v23, v48
	v_mov_b32_e32 v24, v48
	v_mov_b32_e32 v25, v48
	v_mov_b32_e32 v26, v48
	v_mov_b32_e32 v27, v48
	v_mov_b32_e32 v28, v48
	v_mov_b32_e32 v29, v48
	v_mov_b32_e32 v30, v48
	v_mov_b32_e32 v31, v48
	v_mov_b32_e32 v0, v48
	v_mov_b32_e32 v1, v48
	v_mov_b32_e32 v2, v48
	v_mov_b32_e32 v3, v48
	v_mov_b32_e32 v4, v48
	v_mov_b32_e32 v5, v48
	v_mov_b32_e32 v6, v48
	v_mov_b32_e32 v7, v48
	v_mov_b32_e32 v8, v48
	v_mov_b32_e32 v9, v48
	v_mov_b32_e32 v10, v48
	v_mov_b32_e32 v11, v48
	v_mov_b32_e32 v12, v48
	v_mov_b32_e32 v13, v48
	v_mov_b32_e32 v14, v48
	v_mov_b32_e32 v15, v48
	v_mov_b32_e32 v204, v48
	v_mov_b32_e32 v205, v48
	s_waitcnt vmcnt(0)
.LBB0_923:
	s_add_i32 s30, s61, 2
	s_cmpk_gt_u32 s61, 0xfd
	s_cselect_b64 s[44:45], -1, 0
	s_and_b64 vcc, exec, s[44:45]
	s_cbranch_vccnz .LBB0_925
	s_and_b32 s6, s30, 2
	s_mulk_i32 s6, 0x5800
	s_add_i32 s6, s6, 0
	v_add_u32_e32 v84, s6, v238
	v_add_u32_e32 v85, s6, v239
	v_add_u32_e32 v86, s6, v240
	s_waitcnt vmcnt(4)
	ds_write_b128 v84, v[142:145]
	ds_write_b64 v85, v[188:189] offset:128
	s_waitcnt vmcnt(3)
	ds_write_b128 v86, v[146:149] offset:13312
